# P7 packed fp32 arithmetic + output stores left in flight across items; grid barrier: non-leader workgroups wait on the top-level generation word directly (one hop less)
# speedup vs baseline: 1.0109x; 1.0109x over previous
.LBB0_113:
	s_or_b64 exec, exec, s[16:17]
	v_cvt_f32_u32_e32 v5, v3
	s_waitcnt vmcnt(0)
	v_readfirstlane_b32 s2, v4
	v_sub_u32_e32 v4, 0, v3
	v_rcp_iflag_f32_e32 v5, v5
	v_add_u32_e32 v6, s2, v2
	v_mul_f32_e32 v5, 0x4f7ffffe, v5
	v_cvt_u32_f32_e32 v5, v5
	v_mul_lo_u32 v2, v4, v5
	v_mul_hi_u32 v2, v5, v2
	v_add_u32_e32 v2, v5, v2
	v_mul_hi_u32 v2, v6, v2
	v_mul_lo_u32 v4, v2, v3
	v_sub_u32_e32 v4, v6, v4
	v_add_u32_e32 v5, 1, v2
	v_cmp_ge_u32_e32 vcc, v4, v3
	s_nop 1
	v_cndmask_b32_e32 v2, v2, v5, vcc
	v_sub_u32_e32 v5, v4, v3
	v_cndmask_b32_e32 v4, v4, v5, vcc
	v_add_u32_e32 v5, 1, v2
	v_cmp_ge_u32_e32 vcc, v4, v3
	v_add_u32_e32 v4, 1, v6
	s_nop 0
	v_cndmask_b32_e32 v2, v2, v5, vcc
	v_mul_lo_u32 v5, v3, v2
	v_add_u32_e32 v3, v5, v3
	v_cmp_ne_u32_e32 vcc, v4, v3
	s_and_saveexec_b64 s[2:3], vcc
	s_xor_b64 s[10:11], exec, s[2:3]
	s_cbranch_execz .LBB0_127
	s_waitcnt lgkmcnt(0)
	v_mov_b32_e32 v1, 0x3500
	global_load_dword v1, v1, s[60:61] sc1
	s_add_u32 s20, s60, 0x3500
	s_addc_u32 s21, s61, 0
	s_waitcnt vmcnt(0)
	v_cmp_eq_u32_e32 vcc, v1, v2
	s_and_saveexec_b64 s[16:17], vcc
	s_cbranch_execz .LBB0_126
	s_add_u32 s18, s88, 0xc67d200
	s_addc_u32 s19, s89, 0
	s_mov_b32 s2, 1
	s_mov_b64 s[22:23], 0
	v_mov_b32_e32 v1, 0
	s_branch .LBB0_117

.LBB0_144:
	s_or_b64 exec, exec, s[10:11]
	s_mov_b64 s[10:11], exec
	v_mbcnt_lo_u32_b32 v1, s10, 0
	v_mbcnt_hi_u32_b32 v1, s11, v1
	v_cmp_eq_u32_e32 vcc, 0, v1
	s_waitcnt vmcnt(0)
	buffer_inv sc1
	s_and_saveexec_b64 s[16:17], vcc
	s_cbranch_execz .LBB0_146
	s_bcnt1_i32_b64 s2, s[10:11]
	v_mov_b32_e32 v1, 0x2000
	v_mov_b32_e32 v2, s2
.LBB0_146:
	s_or_b64 exec, exec, s[16:17]
	s_waitcnt vmcnt(0)

.LBB0_330:
	s_or_b64 exec, exec, s[10:11]
	v_cvt_f32_u32_e32 v5, v3
	s_waitcnt vmcnt(0)
	v_readfirstlane_b32 s2, v4
	v_sub_u32_e32 v4, 0, v3
	v_rcp_iflag_f32_e32 v5, v5
	v_add_u32_e32 v6, s2, v2
	v_mul_f32_e32 v5, 0x4f7ffffe, v5
	v_cvt_u32_f32_e32 v5, v5
	v_mul_lo_u32 v2, v4, v5
	v_mul_hi_u32 v2, v5, v2
	v_add_u32_e32 v2, v5, v2
	v_mul_hi_u32 v2, v6, v2
	v_mul_lo_u32 v4, v2, v3
	v_sub_u32_e32 v4, v6, v4
	v_add_u32_e32 v5, 1, v2
	v_cmp_ge_u32_e32 vcc, v4, v3
	s_nop 1
	v_cndmask_b32_e32 v2, v2, v5, vcc
	v_sub_u32_e32 v5, v4, v3
	v_cndmask_b32_e32 v4, v4, v5, vcc
	v_add_u32_e32 v5, 1, v2
	v_cmp_ge_u32_e32 vcc, v4, v3
	v_add_u32_e32 v4, 1, v6
	s_nop 0
	v_cndmask_b32_e32 v2, v2, v5, vcc
	v_mul_lo_u32 v5, v3, v2
	v_add_u32_e32 v3, v5, v3
	v_cmp_ne_u32_e32 vcc, v4, v3
	s_and_saveexec_b64 s[2:3], vcc
	s_xor_b64 s[8:9], exec, s[2:3]
	s_cbranch_execz .LBB0_344
	s_waitcnt lgkmcnt(0)
	v_mov_b32_e32 v1, 0x3500
	global_load_dword v1, v1, s[60:61] sc1
	s_add_u32 s14, s60, 0x3500
	s_addc_u32 s15, s61, 0
	s_waitcnt vmcnt(0)
	v_cmp_eq_u32_e32 vcc, v1, v2
	s_and_saveexec_b64 s[10:11], vcc
	s_cbranch_execz .LBB0_343
	s_add_u32 s12, s88, 0xc67d200
	s_addc_u32 s13, s89, 0
	s_mov_b32 s2, 1
	s_mov_b64 s[16:17], 0
	v_mov_b32_e32 v1, 0
	s_branch .LBB0_334

.LBB0_361:
	s_or_b64 exec, exec, s[8:9]
	s_mov_b64 s[8:9], exec
	v_mbcnt_lo_u32_b32 v1, s8, 0
	v_mbcnt_hi_u32_b32 v1, s9, v1
	v_cmp_eq_u32_e32 vcc, 0, v1
	s_waitcnt vmcnt(0)
	buffer_inv sc1
	s_and_saveexec_b64 s[10:11], vcc
	s_cbranch_execz .LBB0_363
	s_bcnt1_i32_b64 s2, s[8:9]
	v_mov_b32_e32 v1, 0x2000
	v_mov_b32_e32 v2, s2
.LBB0_363:
	s_or_b64 exec, exec, s[10:11]
	s_waitcnt vmcnt(0)

.LBB0_475:
	s_or_b64 exec, exec, s[8:9]
	s_mov_b64 s[8:9], exec
	v_mbcnt_lo_u32_b32 v1, s8, 0
	v_mbcnt_hi_u32_b32 v1, s9, v1
	v_cmp_eq_u32_e32 vcc, 0, v1
	s_waitcnt vmcnt(0)
	buffer_inv sc1
	s_and_saveexec_b64 s[10:11], vcc
	s_cbranch_execz .LBB0_477
	s_bcnt1_i32_b64 s2, s[8:9]
	v_mov_b32_e32 v1, 0x2000
	v_mov_b32_e32 v2, s2
.LBB0_477:
	s_or_b64 exec, exec, s[10:11]
	s_waitcnt vmcnt(0)

.LBB0_600:
	s_or_b64 exec, exec, s[10:11]
	v_cvt_f32_u32_e32 v6, v4
	s_waitcnt vmcnt(0)
	v_readfirstlane_b32 s2, v5
	v_sub_u32_e32 v5, 0, v4
	v_rcp_iflag_f32_e32 v6, v6
	v_add_u32_e32 v7, s2, v3
	v_mul_f32_e32 v6, 0x4f7ffffe, v6
	v_cvt_u32_f32_e32 v6, v6
	v_mul_lo_u32 v3, v5, v6
	v_mul_hi_u32 v3, v6, v3
	v_add_u32_e32 v3, v6, v3
	v_mul_hi_u32 v3, v7, v3
	v_mul_lo_u32 v5, v3, v4
	v_sub_u32_e32 v5, v7, v5
	v_add_u32_e32 v6, 1, v3
	v_cmp_ge_u32_e32 vcc, v5, v4
	s_nop 1
	v_cndmask_b32_e32 v3, v3, v6, vcc
	v_sub_u32_e32 v6, v5, v4
	v_cndmask_b32_e32 v5, v5, v6, vcc
	v_add_u32_e32 v6, 1, v3
	v_cmp_ge_u32_e32 vcc, v5, v4
	v_add_u32_e32 v5, 1, v7
	s_nop 0
	v_cndmask_b32_e32 v3, v3, v6, vcc
	v_mul_lo_u32 v6, v4, v3
	v_add_u32_e32 v4, v6, v4
	v_cmp_ne_u32_e32 vcc, v5, v4
	s_and_saveexec_b64 s[2:3], vcc
	s_xor_b64 s[8:9], exec, s[2:3]
	s_cbranch_execz .LBB0_614
	s_waitcnt lgkmcnt(0)
	v_mov_b32_e32 v2, 0x3500
	global_load_dword v2, v2, s[60:61] sc1
	s_add_u32 s14, s60, 0x3500
	s_addc_u32 s15, s61, 0
	s_waitcnt vmcnt(0)
	v_cmp_eq_u32_e32 vcc, v2, v3
	s_and_saveexec_b64 s[10:11], vcc
	s_cbranch_execz .LBB0_613
	s_add_u32 s12, s88, 0xc67d200
	s_addc_u32 s13, s89, 0
	s_mov_b32 s2, 1
	s_mov_b64 s[16:17], 0
	v_mov_b32_e32 v2, 0
	s_branch .LBB0_604

.LBB0_631:
	s_or_b64 exec, exec, s[8:9]
	s_mov_b64 s[8:9], exec
	v_mbcnt_lo_u32_b32 v2, s8, 0
	v_mbcnt_hi_u32_b32 v2, s9, v2
	v_cmp_eq_u32_e32 vcc, 0, v2
	s_waitcnt vmcnt(0)
	buffer_inv sc1
	s_and_saveexec_b64 s[10:11], vcc
	s_cbranch_execz .LBB0_633
	s_bcnt1_i32_b64 s2, s[8:9]
	v_mov_b32_e32 v2, 0x2000
	v_mov_b32_e32 v3, s2
.LBB0_633:
	s_or_b64 exec, exec, s[10:11]
	s_waitcnt vmcnt(0)

.LBB0_660:
	s_or_b64 exec, exec, s[8:9]
	v_cvt_f32_u32_e32 v6, v4
	s_waitcnt vmcnt(0)
	v_readfirstlane_b32 s2, v5
	v_sub_u32_e32 v5, 0, v4
	v_rcp_iflag_f32_e32 v6, v6
	v_add_u32_e32 v7, s2, v3
	v_mul_f32_e32 v6, 0x4f7ffffe, v6
	v_cvt_u32_f32_e32 v6, v6
	v_mul_lo_u32 v3, v5, v6
	v_mul_hi_u32 v3, v6, v3
	v_add_u32_e32 v3, v6, v3
	v_mul_hi_u32 v3, v7, v3
	v_mul_lo_u32 v5, v3, v4
	v_sub_u32_e32 v5, v7, v5
	v_add_u32_e32 v6, 1, v3
	v_cmp_ge_u32_e32 vcc, v5, v4
	s_nop 1
	v_cndmask_b32_e32 v3, v3, v6, vcc
	v_sub_u32_e32 v6, v5, v4
	v_cndmask_b32_e32 v5, v5, v6, vcc
	v_add_u32_e32 v6, 1, v3
	v_cmp_ge_u32_e32 vcc, v5, v4
	v_add_u32_e32 v5, 1, v7
	s_nop 0
	v_cndmask_b32_e32 v3, v3, v6, vcc
	v_mul_lo_u32 v6, v4, v3
	v_add_u32_e32 v4, v6, v4
	v_cmp_ne_u32_e32 vcc, v5, v4
	s_and_saveexec_b64 s[2:3], vcc
	s_xor_b64 s[6:7], exec, s[2:3]
	s_cbranch_execz .LBB0_674
	s_waitcnt lgkmcnt(0)
	v_mov_b32_e32 v2, 0x3500
	global_load_dword v2, v2, s[60:61] sc1
	s_add_u32 s12, s60, 0x3500
	s_addc_u32 s13, s61, 0
	s_waitcnt vmcnt(0)
	v_cmp_eq_u32_e32 vcc, v2, v3
	s_and_saveexec_b64 s[8:9], vcc
	s_cbranch_execz .LBB0_673
	s_add_u32 s10, s88, 0xc67d200
	s_addc_u32 s11, s89, 0
	s_mov_b32 s2, 1
	s_mov_b64 s[14:15], 0
	v_mov_b32_e32 v2, 0
	s_branch .LBB0_664

.LBB0_691:
	s_or_b64 exec, exec, s[6:7]
	s_mov_b64 s[6:7], exec
	v_mbcnt_lo_u32_b32 v2, s6, 0
	v_mbcnt_hi_u32_b32 v2, s7, v2
	v_cmp_eq_u32_e32 vcc, 0, v2
	s_waitcnt vmcnt(0)
	buffer_inv sc1
	s_and_saveexec_b64 s[8:9], vcc
	s_cbranch_execz .LBB0_693
	s_bcnt1_i32_b64 s2, s[6:7]
	v_mov_b32_e32 v2, 0x2000
	v_mov_b32_e32 v3, s2
.LBB0_693:
	s_or_b64 exec, exec, s[8:9]
	s_waitcnt vmcnt(0)

.LBB0_742:
	s_or_b64 exec, exec, s[12:13]
	v_cvt_f32_u32_e32 v6, v4
	s_waitcnt vmcnt(0)
	v_readfirstlane_b32 s2, v5
	v_sub_u32_e32 v5, 0, v4
	v_rcp_iflag_f32_e32 v6, v6
	v_add_u32_e32 v7, s2, v3
	v_mul_f32_e32 v6, 0x4f7ffffe, v6
	v_cvt_u32_f32_e32 v6, v6
	v_mul_lo_u32 v3, v5, v6
	v_mul_hi_u32 v3, v6, v3
	v_add_u32_e32 v3, v6, v3
	v_mul_hi_u32 v3, v7, v3
	v_mul_lo_u32 v5, v3, v4
	v_sub_u32_e32 v5, v7, v5
	v_add_u32_e32 v6, 1, v3
	v_cmp_ge_u32_e32 vcc, v5, v4
	s_nop 1
	v_cndmask_b32_e32 v3, v3, v6, vcc
	v_sub_u32_e32 v6, v5, v4
	v_cndmask_b32_e32 v5, v5, v6, vcc
	v_add_u32_e32 v6, 1, v3
	v_cmp_ge_u32_e32 vcc, v5, v4
	v_add_u32_e32 v5, 1, v7
	s_nop 0
	v_cndmask_b32_e32 v3, v3, v6, vcc
	v_mul_lo_u32 v6, v4, v3
	v_add_u32_e32 v4, v6, v4
	v_cmp_ne_u32_e32 vcc, v5, v4
	s_and_saveexec_b64 s[2:3], vcc
	s_xor_b64 s[10:11], exec, s[2:3]
	s_cbranch_execz .LBB0_756
	s_waitcnt lgkmcnt(0)
	v_mov_b32_e32 v2, 0x3500
	global_load_dword v2, v2, s[60:61] sc1
	s_add_u32 s16, s60, 0x3500
	s_addc_u32 s17, s61, 0
	s_waitcnt vmcnt(0)
	v_cmp_eq_u32_e32 vcc, v2, v3
	s_and_saveexec_b64 s[12:13], vcc
	s_cbranch_execz .LBB0_755
	s_add_u32 s14, s88, 0xc67d200
	s_addc_u32 s15, s89, 0
	s_mov_b32 s2, 1
	s_mov_b64 s[18:19], 0
	v_mov_b32_e32 v2, 0
	s_branch .LBB0_746

.LBB0_773:
	s_or_b64 exec, exec, s[10:11]
	s_mov_b64 s[10:11], exec
	v_mbcnt_lo_u32_b32 v2, s10, 0
	v_mbcnt_hi_u32_b32 v2, s11, v2
	v_cmp_eq_u32_e32 vcc, 0, v2
	s_waitcnt vmcnt(0)
	buffer_inv sc1
	s_and_saveexec_b64 s[12:13], vcc
	s_cbranch_execz .LBB0_775
	s_bcnt1_i32_b64 s2, s[10:11]
	v_mov_b32_e32 v2, 0x2000
	v_mov_b32_e32 v3, s2
.LBB0_775:
	s_or_b64 exec, exec, s[12:13]
	s_waitcnt vmcnt(0)

.LBB0_777:
	s_cmp_lt_i32 s90, 8
	s_cselect_b64 s[2:3], -1, 0
	s_add_u32 s36, s88, 0x115d000
	s_addc_u32 s37, s89, 0
	s_and_b64 s[18:19], s[2:3], s[0:1]
	s_andn2_b64 vcc, exec, s[18:19]
	s_cbranch_vccnz .LBB0_852
	s_cmpk_gt_i32 s58, 0x47f
	s_cbranch_scc1 .LBB0_851
	s_waitcnt vmcnt(0)
	v_readfirstlane_b32 s32, v0
	v_and_b32_e32 v2, 63, v0
	s_mov_b32 s33, 0xbfb8aa3b
	s_mov_b32 s35, 0x3f317217
	s_mov_b32 s36, 0x3377d1cf
	s_mov_b32 s37, 0x3d800000
	s_lshr_b32 s32, s32, 6
	v_lshlrev_b32_e32 v3, 3, v2
	v_lshlrev_b32_e32 v2, 2, v2
	s_mov_b32 s34, s58
	s_mov_b32 s50, 0
	s_mul_hi_u32 s38, s34, 0x1c71c72
	s_mul_i32 s92, s38, 144
	s_sub_i32 s92, s34, s92
	s_mul_hi_u32 s40, s92, 0x71c71c8
	s_mul_i32 s93, s40, 36
	s_sub_i32 s39, s92, s93
	s_lshl_b32 s92, s38, 8
	s_lshl_b32 s93, s39, 6
	s_add_i32 s92, s92, s93
	s_addk_i32 s92, 0x4000
	s_lshl_b32 s94, s38, 11
	s_add_i32 s94, s94, s93
	s_addk_i32 s94, 0xff00
	s_cmp_lt_u32 s39, 4
	s_cselect_b32 s41, s92, s94
	s_lshl_b32 s92, s32, 3
	s_add_i32 s41, s41, s92
	s_lshl_b32 s95, s40, 8
	s_mul_i32 s92, s41, 0x1800
	s_add_u32 s92, s92, s95
	s_add_u32 s42, s96, s92
	s_addc_u32 s43, s97, 0
	s_lshl_b32 s92, s41, 10
	s_add_u32 s92, s92, s95
	s_add_u32 s44, s88, 0xa27d000
	s_addc_u32 s45, s89, 0
	s_add_u32 s44, s44, s92
	s_addc_u32 s45, s45, 0
	s_add_u32 s46, s44, 0x1000000
	s_addc_u32 s47, s45, 0
	s_lshl_b32 s92, s41, 7
	s_add_u32 s48, s88, 0xf1d000
	s_addc_u32 s49, s89, 0
	s_add_u32 s48, s48, s92
	s_addc_u32 s49, s49, 0
	s_lshl_b32 s95, s40, 9
	v_readlane_b32 s52, v251, 18
	v_readlane_b32 s53, v251, 19
	s_nop 3
	s_add_u32 s52, s52, s95
	s_addc_u32 s53, s53, 0
	global_load_dwordx2 v[10:11], v3, s[52:53]
	global_load_dwordx2 v[12:13], v3, s[52:53] offset:2048
	s_add_u32 s52, s52, 0x1000
	s_addc_u32 s53, s53, 0
	global_load_dwordx2 v[14:15], v3, s[52:53]
	global_load_dwordx2 v[16:17], v3, s[52:53] offset:2048
	s_add_u32 s52, s52, 0x1000
	s_addc_u32 s53, s53, 0
	global_load_dwordx2 v[18:19], v3, s[52:53]
	global_load_dwordx2 v[20:21], v3, s[52:53] offset:2048
	s_add_u32 s52, s52, 0x1000
	s_addc_u32 s53, s53, 0
	global_load_dwordx2 v[22:23], v3, s[52:53]
	global_load_dwordx2 v[24:25], v3, s[52:53] offset:2048
	s_add_u32 s52, s52, 0x1000
	s_addc_u32 s53, s53, 0
	global_load_dwordx2 v[26:27], v3, s[52:53]
	global_load_dwordx2 v[28:29], v3, s[52:53] offset:2048
	s_add_u32 s52, s52, 0x1000
	s_addc_u32 s53, s53, 0
	global_load_dwordx2 v[30:31], v3, s[52:53]
	global_load_dwordx2 v[32:33], v3, s[52:53] offset:2048
	s_add_u32 s52, s52, 0x1000
	s_addc_u32 s53, s53, 0
	global_load_dwordx2 v[34:35], v3, s[52:53]
	global_load_dwordx2 v[36:37], v3, s[52:53] offset:2048
	s_add_u32 s52, s52, 0x1000
	s_addc_u32 s53, s53, 0
	global_load_dwordx2 v[38:39], v3, s[52:53]
	global_load_dwordx2 v[40:41], v3, s[52:53] offset:2048
	v_readlane_b32 s52, v251, 24
	v_readlane_b32 s53, v251, 25
	s_nop 3
	s_add_u32 s52, s52, s95
	s_addc_u32 s53, s53, 0
	global_load_dwordx2 v[42:43], v3, s[52:53]
	global_load_dwordx2 v[44:45], v3, s[52:53] offset:2048
	s_add_u32 s52, s52, 0x1000
	s_addc_u32 s53, s53, 0
	global_load_dwordx2 v[46:47], v3, s[52:53]
	global_load_dwordx2 v[48:49], v3, s[52:53] offset:2048
	s_add_u32 s52, s52, 0x1000
	s_addc_u32 s53, s53, 0
	global_load_dwordx2 v[50:51], v3, s[52:53]
	global_load_dwordx2 v[52:53], v3, s[52:53] offset:2048
	s_add_u32 s52, s52, 0x1000
	s_addc_u32 s53, s53, 0
	global_load_dwordx2 v[54:55], v3, s[52:53]
	global_load_dwordx2 v[56:57], v3, s[52:53] offset:2048
	s_add_u32 s52, s52, 0x1000
	s_addc_u32 s53, s53, 0
	global_load_dwordx2 v[58:59], v3, s[52:53]
	global_load_dwordx2 v[60:61], v3, s[52:53] offset:2048
	s_add_u32 s52, s52, 0x1000
	s_addc_u32 s53, s53, 0
	global_load_dwordx2 v[62:63], v3, s[52:53]
	global_load_dwordx2 v[64:65], v3, s[52:53] offset:2048
	s_add_u32 s52, s52, 0x1000
	s_addc_u32 s53, s53, 0
	global_load_dwordx2 v[66:67], v3, s[52:53]
	global_load_dwordx2 v[68:69], v3, s[52:53] offset:2048
	s_add_u32 s52, s52, 0x1000
	s_addc_u32 s53, s53, 0
	global_load_dwordx2 v[70:71], v3, s[52:53]
	global_load_dwordx2 v[72:73], v3, s[52:53] offset:2048
	v_readlane_b32 s52, v251, 20
	v_readlane_b32 s53, v251, 21
	s_nop 3
	s_add_u32 s52, s52, s95
	s_addc_u32 s53, s53, 0
	global_load_dwordx2 v[74:75], v3, s[52:53]
	v_readlane_b32 s52, v251, 26
	v_readlane_b32 s53, v251, 27
	s_nop 3
	s_add_u32 s52, s52, s95
	s_addc_u32 s53, s53, 0
	global_load_dwordx2 v[76:77], v3, s[52:53]
	s_load_dwordx16 s[0:15], s[48:49], 0x0
	s_load_dwordx16 s[64:79], s[48:49], 0x40
	s_mov_b64 s[52:53], s[42:43]
	global_load_dword v200, v2, s[52:53] offset:1024
	s_add_u32 s52, s52, 0x1800
	s_addc_u32 s53, s53, 0
	global_load_dword v201, v2, s[52:53] offset:1024
	s_add_u32 s52, s52, 0x1800
	s_addc_u32 s53, s53, 0
	global_load_dword v202, v2, s[52:53] offset:1024
	s_add_u32 s52, s52, 0x1800
	s_addc_u32 s53, s53, 0
	global_load_dword v203, v2, s[52:53] offset:1024
	s_add_u32 s52, s52, 0x1800
	s_addc_u32 s53, s53, 0
	global_load_dword v204, v2, s[52:53] offset:1024
	s_add_u32 s52, s52, 0x1800
	s_addc_u32 s53, s53, 0
	global_load_dword v205, v2, s[52:53] offset:1024
	s_add_u32 s52, s52, 0x1800
	s_addc_u32 s53, s53, 0
	global_load_dword v206, v2, s[52:53] offset:1024
	s_add_u32 s52, s52, 0x1800
	s_addc_u32 s53, s53, 0
	global_load_dword v207, v2, s[52:53] offset:1024
	s_cmp_lt_u32 s39, 4
	s_cbranch_scc1 .Lp7_noq_load_first
	s_mov_b64 s[52:53], s[42:43]
	global_load_dword v208, v2, s[52:53]
	s_add_u32 s52, s52, 0x1800
	s_addc_u32 s53, s53, 0
	global_load_dword v209, v2, s[52:53]
	s_add_u32 s52, s52, 0x1800
	s_addc_u32 s53, s53, 0
	global_load_dword v210, v2, s[52:53]
	s_add_u32 s52, s52, 0x1800
	s_addc_u32 s53, s53, 0
	global_load_dword v211, v2, s[52:53]
	s_add_u32 s52, s52, 0x1800
	s_addc_u32 s53, s53, 0
	global_load_dword v212, v2, s[52:53]
	s_add_u32 s52, s52, 0x1800
	s_addc_u32 s53, s53, 0
	global_load_dword v213, v2, s[52:53]
	s_add_u32 s52, s52, 0x1800
	s_addc_u32 s53, s53, 0
	global_load_dword v214, v2, s[52:53]
	s_add_u32 s52, s52, 0x1800
	s_addc_u32 s53, s53, 0
	global_load_dword v215, v2, s[52:53]

.Lp7_item:
	v_mov_b32_e32 v80, v200
	v_mov_b32_e32 v81, v201
	v_mov_b32_e32 v82, v202
	v_mov_b32_e32 v83, v203
	v_mov_b32_e32 v84, v204
	v_mov_b32_e32 v85, v205
	v_mov_b32_e32 v86, v206
	v_mov_b32_e32 v87, v207
	v_mov_b32_e32 v88, v208
	v_mov_b32_e32 v89, v209
	v_mov_b32_e32 v90, v210
	v_mov_b32_e32 v91, v211
	v_mov_b32_e32 v92, v212
	v_mov_b32_e32 v93, v213
	v_mov_b32_e32 v94, v214
	v_mov_b32_e32 v95, v215
	s_waitcnt lgkmcnt(0)
	v_pk_fma_f32 v[128:129], v[10:11], s[0:1], v[74:75] op_sel_hi:[1,0,1]
	v_pk_fma_f32 v[128:129], v[12:13], s[0:1], v[128:129] op_sel:[0,1,0] op_sel_hi:[1,1,1]
	v_pk_fma_f32 v[128:129], v[14:15], s[2:3], v[128:129] op_sel_hi:[1,0,1]
	v_pk_fma_f32 v[128:129], v[16:17], s[2:3], v[128:129] op_sel:[0,1,0] op_sel_hi:[1,1,1]
	v_pk_fma_f32 v[128:129], v[18:19], s[4:5], v[128:129] op_sel_hi:[1,0,1]
	v_pk_fma_f32 v[128:129], v[20:21], s[4:5], v[128:129] op_sel:[0,1,0] op_sel_hi:[1,1,1]
	v_pk_fma_f32 v[128:129], v[22:23], s[6:7], v[128:129] op_sel_hi:[1,0,1]
	v_pk_fma_f32 v[128:129], v[24:25], s[6:7], v[128:129] op_sel:[0,1,0] op_sel_hi:[1,1,1]
	v_pk_fma_f32 v[128:129], v[26:27], s[8:9], v[128:129] op_sel_hi:[1,0,1]
	v_pk_fma_f32 v[128:129], v[28:29], s[8:9], v[128:129] op_sel:[0,1,0] op_sel_hi:[1,1,1]
	v_pk_fma_f32 v[128:129], v[30:31], s[10:11], v[128:129] op_sel_hi:[1,0,1]
	v_pk_fma_f32 v[128:129], v[32:33], s[10:11], v[128:129] op_sel:[0,1,0] op_sel_hi:[1,1,1]
	v_pk_fma_f32 v[128:129], v[34:35], s[12:13], v[128:129] op_sel_hi:[1,0,1]
	v_pk_fma_f32 v[128:129], v[36:37], s[12:13], v[128:129] op_sel:[0,1,0] op_sel_hi:[1,1,1]
	v_pk_fma_f32 v[128:129], v[38:39], s[14:15], v[128:129] op_sel_hi:[1,0,1]
	v_pk_fma_f32 v[128:129], v[40:41], s[14:15], v[128:129] op_sel:[0,1,0] op_sel_hi:[1,1,1]
	s_add_u32 s48, s48, 0x80
	s_addc_u32 s49, s49, 0
	s_load_dwordx16 s[0:15], s[48:49], 0x0
	v_pk_fma_f32 v[130:131], v[42:43], s[64:65], v[76:77] op_sel_hi:[1,0,1]
	v_pk_fma_f32 v[130:131], v[44:45], s[64:65], v[130:131] op_sel:[0,1,0] op_sel_hi:[1,1,1]
	v_pk_fma_f32 v[130:131], v[46:47], s[66:67], v[130:131] op_sel_hi:[1,0,1]
	v_pk_fma_f32 v[130:131], v[48:49], s[66:67], v[130:131] op_sel:[0,1,0] op_sel_hi:[1,1,1]
	v_pk_fma_f32 v[130:131], v[50:51], s[68:69], v[130:131] op_sel_hi:[1,0,1]
	v_pk_fma_f32 v[130:131], v[52:53], s[68:69], v[130:131] op_sel:[0,1,0] op_sel_hi:[1,1,1]
	v_pk_fma_f32 v[130:131], v[54:55], s[70:71], v[130:131] op_sel_hi:[1,0,1]
	v_pk_fma_f32 v[130:131], v[56:57], s[70:71], v[130:131] op_sel:[0,1,0] op_sel_hi:[1,1,1]
	v_pk_fma_f32 v[130:131], v[58:59], s[72:73], v[130:131] op_sel_hi:[1,0,1]
	v_pk_fma_f32 v[130:131], v[60:61], s[72:73], v[130:131] op_sel:[0,1,0] op_sel_hi:[1,1,1]
	v_pk_fma_f32 v[130:131], v[62:63], s[74:75], v[130:131] op_sel_hi:[1,0,1]
	v_pk_fma_f32 v[130:131], v[64:65], s[74:75], v[130:131] op_sel:[0,1,0] op_sel_hi:[1,1,1]
	v_pk_fma_f32 v[130:131], v[66:67], s[76:77], v[130:131] op_sel_hi:[1,0,1]
	v_pk_fma_f32 v[130:131], v[68:69], s[76:77], v[130:131] op_sel:[0,1,0] op_sel_hi:[1,1,1]
	v_pk_fma_f32 v[130:131], v[70:71], s[78:79], v[130:131] op_sel_hi:[1,0,1]
	v_pk_fma_f32 v[130:131], v[72:73], s[78:79], v[130:131] op_sel:[0,1,0] op_sel_hi:[1,1,1]
	s_load_dwordx16 s[64:79], s[48:49], 0x40
	v_mul_f32_e64 v132, |v128|, s33
	v_mul_f32_e64 v133, |v129|, s33
	v_mul_f32_e64 v134, |v130|, s33
	v_mul_f32_e64 v135, |v131|, s33
	v_exp_f32_e32 v132, v132
	v_exp_f32_e32 v133, v133
	v_exp_f32_e32 v134, v134
	v_exp_f32_e32 v135, v135
	v_pk_add_f32 v[132:133], v[132:133], 1.0 op_sel_hi:[1,0]
	v_pk_add_f32 v[134:135], v[134:135], 1.0 op_sel_hi:[1,0]
	v_log_f32_e32 v136, v132
	v_log_f32_e32 v137, v133
	v_log_f32_e32 v138, v134
	v_log_f32_e32 v139, v135
	v_pk_mul_f32 v[140:141], v[136:137], s[34:35] op_sel:[0,1] op_sel_hi:[1,1]
	v_pk_mul_f32 v[142:143], v[138:139], s[34:35] op_sel:[0,1] op_sel_hi:[1,1]
	v_pk_fma_f32 v[144:145], v[136:137], s[34:35], v[140:141] op_sel:[0,1,0] op_sel_hi:[1,1,1] neg_lo:[0,0,1] neg_hi:[0,0,1]
	v_pk_fma_f32 v[146:147], v[138:139], s[34:35], v[142:143] op_sel:[0,1,0] op_sel_hi:[1,1,1] neg_lo:[0,0,1] neg_hi:[0,0,1]
	v_pk_fma_f32 v[144:145], v[136:137], s[36:37], v[144:145] op_sel_hi:[1,0,1]
	v_pk_fma_f32 v[146:147], v[138:139], s[36:37], v[146:147] op_sel_hi:[1,0,1]
	v_pk_fma_f32 v[144:145], v[136:137], s[34:35], v[144:145] op_sel:[0,1,0] op_sel_hi:[1,1,1]
	v_pk_fma_f32 v[146:147], v[138:139], s[34:35], v[146:147] op_sel:[0,1,0] op_sel_hi:[1,1,1]
	v_min_f32_e32 v128, 0, v128
	v_min_f32_e32 v129, 0, v129
	v_min_f32_e32 v130, 0, v130
	v_min_f32_e32 v131, 0, v131
	v_pk_add_f32 v[128:129], v[128:129], v[144:145] neg_lo:[0,1] neg_hi:[0,1]
	v_pk_add_f32 v[130:131], v[130:131], v[146:147] neg_lo:[0,1] neg_hi:[0,1]
	v_pk_mul_f32 v[96:97], v[128:129], s[36:37] op_sel:[0,1] op_sel_hi:[1,1]
	v_pk_mul_f32 v[112:113], v[130:131], s[36:37] op_sel:[0,1] op_sel_hi:[1,1]
	s_waitcnt lgkmcnt(0)
	v_pk_fma_f32 v[128:129], v[10:11], s[0:1], v[74:75] op_sel_hi:[1,0,1]
	v_pk_fma_f32 v[128:129], v[12:13], s[0:1], v[128:129] op_sel:[0,1,0] op_sel_hi:[1,1,1]
	v_pk_fma_f32 v[128:129], v[14:15], s[2:3], v[128:129] op_sel_hi:[1,0,1]
	v_pk_fma_f32 v[128:129], v[16:17], s[2:3], v[128:129] op_sel:[0,1,0] op_sel_hi:[1,1,1]
	v_pk_fma_f32 v[128:129], v[18:19], s[4:5], v[128:129] op_sel_hi:[1,0,1]
	v_pk_fma_f32 v[128:129], v[20:21], s[4:5], v[128:129] op_sel:[0,1,0] op_sel_hi:[1,1,1]
	v_pk_fma_f32 v[128:129], v[22:23], s[6:7], v[128:129] op_sel_hi:[1,0,1]
	v_pk_fma_f32 v[128:129], v[24:25], s[6:7], v[128:129] op_sel:[0,1,0] op_sel_hi:[1,1,1]
	v_pk_fma_f32 v[128:129], v[26:27], s[8:9], v[128:129] op_sel_hi:[1,0,1]
	v_pk_fma_f32 v[128:129], v[28:29], s[8:9], v[128:129] op_sel:[0,1,0] op_sel_hi:[1,1,1]
	v_pk_fma_f32 v[128:129], v[30:31], s[10:11], v[128:129] op_sel_hi:[1,0,1]
	v_pk_fma_f32 v[128:129], v[32:33], s[10:11], v[128:129] op_sel:[0,1,0] op_sel_hi:[1,1,1]
	v_pk_fma_f32 v[128:129], v[34:35], s[12:13], v[128:129] op_sel_hi:[1,0,1]
	v_pk_fma_f32 v[128:129], v[36:37], s[12:13], v[128:129] op_sel:[0,1,0] op_sel_hi:[1,1,1]
	v_pk_fma_f32 v[128:129], v[38:39], s[14:15], v[128:129] op_sel_hi:[1,0,1]
	v_pk_fma_f32 v[128:129], v[40:41], s[14:15], v[128:129] op_sel:[0,1,0] op_sel_hi:[1,1,1]
	s_add_u32 s48, s48, 0x80
	s_addc_u32 s49, s49, 0
	s_load_dwordx16 s[0:15], s[48:49], 0x0
	v_pk_fma_f32 v[130:131], v[42:43], s[64:65], v[76:77] op_sel_hi:[1,0,1]
	v_pk_fma_f32 v[130:131], v[44:45], s[64:65], v[130:131] op_sel:[0,1,0] op_sel_hi:[1,1,1]
	v_pk_fma_f32 v[130:131], v[46:47], s[66:67], v[130:131] op_sel_hi:[1,0,1]
	v_pk_fma_f32 v[130:131], v[48:49], s[66:67], v[130:131] op_sel:[0,1,0] op_sel_hi:[1,1,1]
	v_pk_fma_f32 v[130:131], v[50:51], s[68:69], v[130:131] op_sel_hi:[1,0,1]
	v_pk_fma_f32 v[130:131], v[52:53], s[68:69], v[130:131] op_sel:[0,1,0] op_sel_hi:[1,1,1]
	v_pk_fma_f32 v[130:131], v[54:55], s[70:71], v[130:131] op_sel_hi:[1,0,1]
	v_pk_fma_f32 v[130:131], v[56:57], s[70:71], v[130:131] op_sel:[0,1,0] op_sel_hi:[1,1,1]
	v_pk_fma_f32 v[130:131], v[58:59], s[72:73], v[130:131] op_sel_hi:[1,0,1]
	v_pk_fma_f32 v[130:131], v[60:61], s[72:73], v[130:131] op_sel:[0,1,0] op_sel_hi:[1,1,1]
	v_pk_fma_f32 v[130:131], v[62:63], s[74:75], v[130:131] op_sel_hi:[1,0,1]
	v_pk_fma_f32 v[130:131], v[64:65], s[74:75], v[130:131] op_sel:[0,1,0] op_sel_hi:[1,1,1]
	v_pk_fma_f32 v[130:131], v[66:67], s[76:77], v[130:131] op_sel_hi:[1,0,1]
	v_pk_fma_f32 v[130:131], v[68:69], s[76:77], v[130:131] op_sel:[0,1,0] op_sel_hi:[1,1,1]
	v_pk_fma_f32 v[130:131], v[70:71], s[78:79], v[130:131] op_sel_hi:[1,0,1]
	v_pk_fma_f32 v[130:131], v[72:73], s[78:79], v[130:131] op_sel:[0,1,0] op_sel_hi:[1,1,1]
	s_load_dwordx16 s[64:79], s[48:49], 0x40
	v_mul_f32_e64 v132, |v128|, s33
	v_mul_f32_e64 v133, |v129|, s33
	v_mul_f32_e64 v134, |v130|, s33
	v_mul_f32_e64 v135, |v131|, s33
	v_exp_f32_e32 v132, v132
	v_exp_f32_e32 v133, v133
	v_exp_f32_e32 v134, v134
	v_exp_f32_e32 v135, v135
	v_pk_add_f32 v[132:133], v[132:133], 1.0 op_sel_hi:[1,0]
	v_pk_add_f32 v[134:135], v[134:135], 1.0 op_sel_hi:[1,0]
	v_log_f32_e32 v136, v132
	v_log_f32_e32 v137, v133
	v_log_f32_e32 v138, v134
	v_log_f32_e32 v139, v135
	v_pk_mul_f32 v[140:141], v[136:137], s[34:35] op_sel:[0,1] op_sel_hi:[1,1]
	v_pk_mul_f32 v[142:143], v[138:139], s[34:35] op_sel:[0,1] op_sel_hi:[1,1]
	v_pk_fma_f32 v[144:145], v[136:137], s[34:35], v[140:141] op_sel:[0,1,0] op_sel_hi:[1,1,1] neg_lo:[0,0,1] neg_hi:[0,0,1]
	v_pk_fma_f32 v[146:147], v[138:139], s[34:35], v[142:143] op_sel:[0,1,0] op_sel_hi:[1,1,1] neg_lo:[0,0,1] neg_hi:[0,0,1]
	v_pk_fma_f32 v[144:145], v[136:137], s[36:37], v[144:145] op_sel_hi:[1,0,1]
	v_pk_fma_f32 v[146:147], v[138:139], s[36:37], v[146:147] op_sel_hi:[1,0,1]
	v_pk_fma_f32 v[144:145], v[136:137], s[34:35], v[144:145] op_sel:[0,1,0] op_sel_hi:[1,1,1]
	v_pk_fma_f32 v[146:147], v[138:139], s[34:35], v[146:147] op_sel:[0,1,0] op_sel_hi:[1,1,1]
	v_min_f32_e32 v128, 0, v128
	v_min_f32_e32 v129, 0, v129
	v_min_f32_e32 v130, 0, v130
	v_min_f32_e32 v131, 0, v131
	v_pk_add_f32 v[128:129], v[128:129], v[144:145] neg_lo:[0,1] neg_hi:[0,1]
	v_pk_add_f32 v[130:131], v[130:131], v[146:147] neg_lo:[0,1] neg_hi:[0,1]
	v_pk_mul_f32 v[98:99], v[128:129], s[36:37] op_sel:[0,1] op_sel_hi:[1,1]
	v_pk_mul_f32 v[114:115], v[130:131], s[36:37] op_sel:[0,1] op_sel_hi:[1,1]
	s_waitcnt lgkmcnt(0)
	v_pk_fma_f32 v[128:129], v[10:11], s[0:1], v[74:75] op_sel_hi:[1,0,1]
	v_pk_fma_f32 v[128:129], v[12:13], s[0:1], v[128:129] op_sel:[0,1,0] op_sel_hi:[1,1,1]
	v_pk_fma_f32 v[128:129], v[14:15], s[2:3], v[128:129] op_sel_hi:[1,0,1]
	v_pk_fma_f32 v[128:129], v[16:17], s[2:3], v[128:129] op_sel:[0,1,0] op_sel_hi:[1,1,1]
	v_pk_fma_f32 v[128:129], v[18:19], s[4:5], v[128:129] op_sel_hi:[1,0,1]
	v_pk_fma_f32 v[128:129], v[20:21], s[4:5], v[128:129] op_sel:[0,1,0] op_sel_hi:[1,1,1]
	v_pk_fma_f32 v[128:129], v[22:23], s[6:7], v[128:129] op_sel_hi:[1,0,1]
	v_pk_fma_f32 v[128:129], v[24:25], s[6:7], v[128:129] op_sel:[0,1,0] op_sel_hi:[1,1,1]
	v_pk_fma_f32 v[128:129], v[26:27], s[8:9], v[128:129] op_sel_hi:[1,0,1]
	v_pk_fma_f32 v[128:129], v[28:29], s[8:9], v[128:129] op_sel:[0,1,0] op_sel_hi:[1,1,1]
	v_pk_fma_f32 v[128:129], v[30:31], s[10:11], v[128:129] op_sel_hi:[1,0,1]
	v_pk_fma_f32 v[128:129], v[32:33], s[10:11], v[128:129] op_sel:[0,1,0] op_sel_hi:[1,1,1]
	v_pk_fma_f32 v[128:129], v[34:35], s[12:13], v[128:129] op_sel_hi:[1,0,1]
	v_pk_fma_f32 v[128:129], v[36:37], s[12:13], v[128:129] op_sel:[0,1,0] op_sel_hi:[1,1,1]
	v_pk_fma_f32 v[128:129], v[38:39], s[14:15], v[128:129] op_sel_hi:[1,0,1]
	v_pk_fma_f32 v[128:129], v[40:41], s[14:15], v[128:129] op_sel:[0,1,0] op_sel_hi:[1,1,1]
	s_add_u32 s48, s48, 0x80
	s_addc_u32 s49, s49, 0
	s_load_dwordx16 s[0:15], s[48:49], 0x0
	v_pk_fma_f32 v[130:131], v[42:43], s[64:65], v[76:77] op_sel_hi:[1,0,1]
	v_pk_fma_f32 v[130:131], v[44:45], s[64:65], v[130:131] op_sel:[0,1,0] op_sel_hi:[1,1,1]
	v_pk_fma_f32 v[130:131], v[46:47], s[66:67], v[130:131] op_sel_hi:[1,0,1]
	v_pk_fma_f32 v[130:131], v[48:49], s[66:67], v[130:131] op_sel:[0,1,0] op_sel_hi:[1,1,1]
	v_pk_fma_f32 v[130:131], v[50:51], s[68:69], v[130:131] op_sel_hi:[1,0,1]
	v_pk_fma_f32 v[130:131], v[52:53], s[68:69], v[130:131] op_sel:[0,1,0] op_sel_hi:[1,1,1]
	v_pk_fma_f32 v[130:131], v[54:55], s[70:71], v[130:131] op_sel_hi:[1,0,1]
	v_pk_fma_f32 v[130:131], v[56:57], s[70:71], v[130:131] op_sel:[0,1,0] op_sel_hi:[1,1,1]
	v_pk_fma_f32 v[130:131], v[58:59], s[72:73], v[130:131] op_sel_hi:[1,0,1]
	v_pk_fma_f32 v[130:131], v[60:61], s[72:73], v[130:131] op_sel:[0,1,0] op_sel_hi:[1,1,1]
	v_pk_fma_f32 v[130:131], v[62:63], s[74:75], v[130:131] op_sel_hi:[1,0,1]
	v_pk_fma_f32 v[130:131], v[64:65], s[74:75], v[130:131] op_sel:[0,1,0] op_sel_hi:[1,1,1]
	v_pk_fma_f32 v[130:131], v[66:67], s[76:77], v[130:131] op_sel_hi:[1,0,1]
	v_pk_fma_f32 v[130:131], v[68:69], s[76:77], v[130:131] op_sel:[0,1,0] op_sel_hi:[1,1,1]
	v_pk_fma_f32 v[130:131], v[70:71], s[78:79], v[130:131] op_sel_hi:[1,0,1]
	v_pk_fma_f32 v[130:131], v[72:73], s[78:79], v[130:131] op_sel:[0,1,0] op_sel_hi:[1,1,1]
	s_load_dwordx16 s[64:79], s[48:49], 0x40
	v_mul_f32_e64 v132, |v128|, s33
	v_mul_f32_e64 v133, |v129|, s33
	v_mul_f32_e64 v134, |v130|, s33
	v_mul_f32_e64 v135, |v131|, s33
	v_exp_f32_e32 v132, v132
	v_exp_f32_e32 v133, v133
	v_exp_f32_e32 v134, v134
	v_exp_f32_e32 v135, v135
	v_pk_add_f32 v[132:133], v[132:133], 1.0 op_sel_hi:[1,0]
	v_pk_add_f32 v[134:135], v[134:135], 1.0 op_sel_hi:[1,0]
	v_log_f32_e32 v136, v132
	v_log_f32_e32 v137, v133
	v_log_f32_e32 v138, v134
	v_log_f32_e32 v139, v135
	v_pk_mul_f32 v[140:141], v[136:137], s[34:35] op_sel:[0,1] op_sel_hi:[1,1]
	v_pk_mul_f32 v[142:143], v[138:139], s[34:35] op_sel:[0,1] op_sel_hi:[1,1]
	v_pk_fma_f32 v[144:145], v[136:137], s[34:35], v[140:141] op_sel:[0,1,0] op_sel_hi:[1,1,1] neg_lo:[0,0,1] neg_hi:[0,0,1]
	v_pk_fma_f32 v[146:147], v[138:139], s[34:35], v[142:143] op_sel:[0,1,0] op_sel_hi:[1,1,1] neg_lo:[0,0,1] neg_hi:[0,0,1]
	v_pk_fma_f32 v[144:145], v[136:137], s[36:37], v[144:145] op_sel_hi:[1,0,1]
	v_pk_fma_f32 v[146:147], v[138:139], s[36:37], v[146:147] op_sel_hi:[1,0,1]
	v_pk_fma_f32 v[144:145], v[136:137], s[34:35], v[144:145] op_sel:[0,1,0] op_sel_hi:[1,1,1]
	v_pk_fma_f32 v[146:147], v[138:139], s[34:35], v[146:147] op_sel:[0,1,0] op_sel_hi:[1,1,1]
	v_min_f32_e32 v128, 0, v128
	v_min_f32_e32 v129, 0, v129
	v_min_f32_e32 v130, 0, v130
	v_min_f32_e32 v131, 0, v131
	v_pk_add_f32 v[128:129], v[128:129], v[144:145] neg_lo:[0,1] neg_hi:[0,1]
	v_pk_add_f32 v[130:131], v[130:131], v[146:147] neg_lo:[0,1] neg_hi:[0,1]
	v_pk_mul_f32 v[100:101], v[128:129], s[36:37] op_sel:[0,1] op_sel_hi:[1,1]
	v_pk_mul_f32 v[116:117], v[130:131], s[36:37] op_sel:[0,1] op_sel_hi:[1,1]
	s_waitcnt lgkmcnt(0)
	v_pk_fma_f32 v[128:129], v[10:11], s[0:1], v[74:75] op_sel_hi:[1,0,1]
	v_pk_fma_f32 v[128:129], v[12:13], s[0:1], v[128:129] op_sel:[0,1,0] op_sel_hi:[1,1,1]
	v_pk_fma_f32 v[128:129], v[14:15], s[2:3], v[128:129] op_sel_hi:[1,0,1]
	v_pk_fma_f32 v[128:129], v[16:17], s[2:3], v[128:129] op_sel:[0,1,0] op_sel_hi:[1,1,1]
	v_pk_fma_f32 v[128:129], v[18:19], s[4:5], v[128:129] op_sel_hi:[1,0,1]
	v_pk_fma_f32 v[128:129], v[20:21], s[4:5], v[128:129] op_sel:[0,1,0] op_sel_hi:[1,1,1]
	v_pk_fma_f32 v[128:129], v[22:23], s[6:7], v[128:129] op_sel_hi:[1,0,1]
	v_pk_fma_f32 v[128:129], v[24:25], s[6:7], v[128:129] op_sel:[0,1,0] op_sel_hi:[1,1,1]
	v_pk_fma_f32 v[128:129], v[26:27], s[8:9], v[128:129] op_sel_hi:[1,0,1]
	v_pk_fma_f32 v[128:129], v[28:29], s[8:9], v[128:129] op_sel:[0,1,0] op_sel_hi:[1,1,1]
	v_pk_fma_f32 v[128:129], v[30:31], s[10:11], v[128:129] op_sel_hi:[1,0,1]
	v_pk_fma_f32 v[128:129], v[32:33], s[10:11], v[128:129] op_sel:[0,1,0] op_sel_hi:[1,1,1]
	v_pk_fma_f32 v[128:129], v[34:35], s[12:13], v[128:129] op_sel_hi:[1,0,1]
	v_pk_fma_f32 v[128:129], v[36:37], s[12:13], v[128:129] op_sel:[0,1,0] op_sel_hi:[1,1,1]
	v_pk_fma_f32 v[128:129], v[38:39], s[14:15], v[128:129] op_sel_hi:[1,0,1]
	v_pk_fma_f32 v[128:129], v[40:41], s[14:15], v[128:129] op_sel:[0,1,0] op_sel_hi:[1,1,1]
	s_add_u32 s48, s48, 0x80
	s_addc_u32 s49, s49, 0
	s_load_dwordx16 s[0:15], s[48:49], 0x0
	v_pk_fma_f32 v[130:131], v[42:43], s[64:65], v[76:77] op_sel_hi:[1,0,1]
	v_pk_fma_f32 v[130:131], v[44:45], s[64:65], v[130:131] op_sel:[0,1,0] op_sel_hi:[1,1,1]
	v_pk_fma_f32 v[130:131], v[46:47], s[66:67], v[130:131] op_sel_hi:[1,0,1]
	v_pk_fma_f32 v[130:131], v[48:49], s[66:67], v[130:131] op_sel:[0,1,0] op_sel_hi:[1,1,1]
	v_pk_fma_f32 v[130:131], v[50:51], s[68:69], v[130:131] op_sel_hi:[1,0,1]
	v_pk_fma_f32 v[130:131], v[52:53], s[68:69], v[130:131] op_sel:[0,1,0] op_sel_hi:[1,1,1]
	v_pk_fma_f32 v[130:131], v[54:55], s[70:71], v[130:131] op_sel_hi:[1,0,1]
	v_pk_fma_f32 v[130:131], v[56:57], s[70:71], v[130:131] op_sel:[0,1,0] op_sel_hi:[1,1,1]
	v_pk_fma_f32 v[130:131], v[58:59], s[72:73], v[130:131] op_sel_hi:[1,0,1]
	v_pk_fma_f32 v[130:131], v[60:61], s[72:73], v[130:131] op_sel:[0,1,0] op_sel_hi:[1,1,1]
	v_pk_fma_f32 v[130:131], v[62:63], s[74:75], v[130:131] op_sel_hi:[1,0,1]
	v_pk_fma_f32 v[130:131], v[64:65], s[74:75], v[130:131] op_sel:[0,1,0] op_sel_hi:[1,1,1]
	v_pk_fma_f32 v[130:131], v[66:67], s[76:77], v[130:131] op_sel_hi:[1,0,1]
	v_pk_fma_f32 v[130:131], v[68:69], s[76:77], v[130:131] op_sel:[0,1,0] op_sel_hi:[1,1,1]
	v_pk_fma_f32 v[130:131], v[70:71], s[78:79], v[130:131] op_sel_hi:[1,0,1]
	v_pk_fma_f32 v[130:131], v[72:73], s[78:79], v[130:131] op_sel:[0,1,0] op_sel_hi:[1,1,1]
	s_load_dwordx16 s[64:79], s[48:49], 0x40
	v_mul_f32_e64 v132, |v128|, s33
	v_mul_f32_e64 v133, |v129|, s33
	v_mul_f32_e64 v134, |v130|, s33
	v_mul_f32_e64 v135, |v131|, s33
	v_exp_f32_e32 v132, v132
	v_exp_f32_e32 v133, v133
	v_exp_f32_e32 v134, v134
	v_exp_f32_e32 v135, v135
	v_pk_add_f32 v[132:133], v[132:133], 1.0 op_sel_hi:[1,0]
	v_pk_add_f32 v[134:135], v[134:135], 1.0 op_sel_hi:[1,0]
	v_log_f32_e32 v136, v132
	v_log_f32_e32 v137, v133
	v_log_f32_e32 v138, v134
	v_log_f32_e32 v139, v135
	v_pk_mul_f32 v[140:141], v[136:137], s[34:35] op_sel:[0,1] op_sel_hi:[1,1]
	v_pk_mul_f32 v[142:143], v[138:139], s[34:35] op_sel:[0,1] op_sel_hi:[1,1]
	v_pk_fma_f32 v[144:145], v[136:137], s[34:35], v[140:141] op_sel:[0,1,0] op_sel_hi:[1,1,1] neg_lo:[0,0,1] neg_hi:[0,0,1]
	v_pk_fma_f32 v[146:147], v[138:139], s[34:35], v[142:143] op_sel:[0,1,0] op_sel_hi:[1,1,1] neg_lo:[0,0,1] neg_hi:[0,0,1]
	v_pk_fma_f32 v[144:145], v[136:137], s[36:37], v[144:145] op_sel_hi:[1,0,1]
	v_pk_fma_f32 v[146:147], v[138:139], s[36:37], v[146:147] op_sel_hi:[1,0,1]
	v_pk_fma_f32 v[144:145], v[136:137], s[34:35], v[144:145] op_sel:[0,1,0] op_sel_hi:[1,1,1]
	v_pk_fma_f32 v[146:147], v[138:139], s[34:35], v[146:147] op_sel:[0,1,0] op_sel_hi:[1,1,1]
	v_min_f32_e32 v128, 0, v128
	v_min_f32_e32 v129, 0, v129
	v_min_f32_e32 v130, 0, v130
	v_min_f32_e32 v131, 0, v131
	v_pk_add_f32 v[128:129], v[128:129], v[144:145] neg_lo:[0,1] neg_hi:[0,1]
	v_pk_add_f32 v[130:131], v[130:131], v[146:147] neg_lo:[0,1] neg_hi:[0,1]
	v_pk_mul_f32 v[102:103], v[128:129], s[36:37] op_sel:[0,1] op_sel_hi:[1,1]
	v_pk_mul_f32 v[118:119], v[130:131], s[36:37] op_sel:[0,1] op_sel_hi:[1,1]
	s_waitcnt lgkmcnt(0)
	v_pk_fma_f32 v[128:129], v[10:11], s[0:1], v[74:75] op_sel_hi:[1,0,1]
	v_pk_fma_f32 v[128:129], v[12:13], s[0:1], v[128:129] op_sel:[0,1,0] op_sel_hi:[1,1,1]
	v_pk_fma_f32 v[128:129], v[14:15], s[2:3], v[128:129] op_sel_hi:[1,0,1]
	v_pk_fma_f32 v[128:129], v[16:17], s[2:3], v[128:129] op_sel:[0,1,0] op_sel_hi:[1,1,1]
	v_pk_fma_f32 v[128:129], v[18:19], s[4:5], v[128:129] op_sel_hi:[1,0,1]
	v_pk_fma_f32 v[128:129], v[20:21], s[4:5], v[128:129] op_sel:[0,1,0] op_sel_hi:[1,1,1]
	v_pk_fma_f32 v[128:129], v[22:23], s[6:7], v[128:129] op_sel_hi:[1,0,1]
	v_pk_fma_f32 v[128:129], v[24:25], s[6:7], v[128:129] op_sel:[0,1,0] op_sel_hi:[1,1,1]
	v_pk_fma_f32 v[128:129], v[26:27], s[8:9], v[128:129] op_sel_hi:[1,0,1]
	v_pk_fma_f32 v[128:129], v[28:29], s[8:9], v[128:129] op_sel:[0,1,0] op_sel_hi:[1,1,1]
	v_pk_fma_f32 v[128:129], v[30:31], s[10:11], v[128:129] op_sel_hi:[1,0,1]
	v_pk_fma_f32 v[128:129], v[32:33], s[10:11], v[128:129] op_sel:[0,1,0] op_sel_hi:[1,1,1]
	v_pk_fma_f32 v[128:129], v[34:35], s[12:13], v[128:129] op_sel_hi:[1,0,1]
	v_pk_fma_f32 v[128:129], v[36:37], s[12:13], v[128:129] op_sel:[0,1,0] op_sel_hi:[1,1,1]
	v_pk_fma_f32 v[128:129], v[38:39], s[14:15], v[128:129] op_sel_hi:[1,0,1]
	v_pk_fma_f32 v[128:129], v[40:41], s[14:15], v[128:129] op_sel:[0,1,0] op_sel_hi:[1,1,1]
	s_add_u32 s48, s48, 0x80
	s_addc_u32 s49, s49, 0
	s_load_dwordx16 s[0:15], s[48:49], 0x0
	v_pk_fma_f32 v[130:131], v[42:43], s[64:65], v[76:77] op_sel_hi:[1,0,1]
	v_pk_fma_f32 v[130:131], v[44:45], s[64:65], v[130:131] op_sel:[0,1,0] op_sel_hi:[1,1,1]
	v_pk_fma_f32 v[130:131], v[46:47], s[66:67], v[130:131] op_sel_hi:[1,0,1]
	v_pk_fma_f32 v[130:131], v[48:49], s[66:67], v[130:131] op_sel:[0,1,0] op_sel_hi:[1,1,1]
	v_pk_fma_f32 v[130:131], v[50:51], s[68:69], v[130:131] op_sel_hi:[1,0,1]
	v_pk_fma_f32 v[130:131], v[52:53], s[68:69], v[130:131] op_sel:[0,1,0] op_sel_hi:[1,1,1]
	v_pk_fma_f32 v[130:131], v[54:55], s[70:71], v[130:131] op_sel_hi:[1,0,1]
	v_pk_fma_f32 v[130:131], v[56:57], s[70:71], v[130:131] op_sel:[0,1,0] op_sel_hi:[1,1,1]
	v_pk_fma_f32 v[130:131], v[58:59], s[72:73], v[130:131] op_sel_hi:[1,0,1]
	v_pk_fma_f32 v[130:131], v[60:61], s[72:73], v[130:131] op_sel:[0,1,0] op_sel_hi:[1,1,1]
	v_pk_fma_f32 v[130:131], v[62:63], s[74:75], v[130:131] op_sel_hi:[1,0,1]
	v_pk_fma_f32 v[130:131], v[64:65], s[74:75], v[130:131] op_sel:[0,1,0] op_sel_hi:[1,1,1]
	v_pk_fma_f32 v[130:131], v[66:67], s[76:77], v[130:131] op_sel_hi:[1,0,1]
	v_pk_fma_f32 v[130:131], v[68:69], s[76:77], v[130:131] op_sel:[0,1,0] op_sel_hi:[1,1,1]
	v_pk_fma_f32 v[130:131], v[70:71], s[78:79], v[130:131] op_sel_hi:[1,0,1]
	v_pk_fma_f32 v[130:131], v[72:73], s[78:79], v[130:131] op_sel:[0,1,0] op_sel_hi:[1,1,1]
	s_load_dwordx16 s[64:79], s[48:49], 0x40
	v_mul_f32_e64 v132, |v128|, s33
	v_mul_f32_e64 v133, |v129|, s33
	v_mul_f32_e64 v134, |v130|, s33
	v_mul_f32_e64 v135, |v131|, s33
	v_exp_f32_e32 v132, v132
	v_exp_f32_e32 v133, v133
	v_exp_f32_e32 v134, v134
	v_exp_f32_e32 v135, v135
	v_pk_add_f32 v[132:133], v[132:133], 1.0 op_sel_hi:[1,0]
	v_pk_add_f32 v[134:135], v[134:135], 1.0 op_sel_hi:[1,0]
	v_log_f32_e32 v136, v132
	v_log_f32_e32 v137, v133
	v_log_f32_e32 v138, v134
	v_log_f32_e32 v139, v135
	v_pk_mul_f32 v[140:141], v[136:137], s[34:35] op_sel:[0,1] op_sel_hi:[1,1]
	v_pk_mul_f32 v[142:143], v[138:139], s[34:35] op_sel:[0,1] op_sel_hi:[1,1]
	v_pk_fma_f32 v[144:145], v[136:137], s[34:35], v[140:141] op_sel:[0,1,0] op_sel_hi:[1,1,1] neg_lo:[0,0,1] neg_hi:[0,0,1]
	v_pk_fma_f32 v[146:147], v[138:139], s[34:35], v[142:143] op_sel:[0,1,0] op_sel_hi:[1,1,1] neg_lo:[0,0,1] neg_hi:[0,0,1]
	v_pk_fma_f32 v[144:145], v[136:137], s[36:37], v[144:145] op_sel_hi:[1,0,1]
	v_pk_fma_f32 v[146:147], v[138:139], s[36:37], v[146:147] op_sel_hi:[1,0,1]
	v_pk_fma_f32 v[144:145], v[136:137], s[34:35], v[144:145] op_sel:[0,1,0] op_sel_hi:[1,1,1]
	v_pk_fma_f32 v[146:147], v[138:139], s[34:35], v[146:147] op_sel:[0,1,0] op_sel_hi:[1,1,1]
	v_min_f32_e32 v128, 0, v128
	v_min_f32_e32 v129, 0, v129
	v_min_f32_e32 v130, 0, v130
	v_min_f32_e32 v131, 0, v131
	v_pk_add_f32 v[128:129], v[128:129], v[144:145] neg_lo:[0,1] neg_hi:[0,1]
	v_pk_add_f32 v[130:131], v[130:131], v[146:147] neg_lo:[0,1] neg_hi:[0,1]
	v_pk_mul_f32 v[104:105], v[128:129], s[36:37] op_sel:[0,1] op_sel_hi:[1,1]
	v_pk_mul_f32 v[120:121], v[130:131], s[36:37] op_sel:[0,1] op_sel_hi:[1,1]
	s_waitcnt lgkmcnt(0)
	v_pk_fma_f32 v[128:129], v[10:11], s[0:1], v[74:75] op_sel_hi:[1,0,1]
	v_pk_fma_f32 v[128:129], v[12:13], s[0:1], v[128:129] op_sel:[0,1,0] op_sel_hi:[1,1,1]
	v_pk_fma_f32 v[128:129], v[14:15], s[2:3], v[128:129] op_sel_hi:[1,0,1]
	v_pk_fma_f32 v[128:129], v[16:17], s[2:3], v[128:129] op_sel:[0,1,0] op_sel_hi:[1,1,1]
	v_pk_fma_f32 v[128:129], v[18:19], s[4:5], v[128:129] op_sel_hi:[1,0,1]
	v_pk_fma_f32 v[128:129], v[20:21], s[4:5], v[128:129] op_sel:[0,1,0] op_sel_hi:[1,1,1]
	v_pk_fma_f32 v[128:129], v[22:23], s[6:7], v[128:129] op_sel_hi:[1,0,1]
	v_pk_fma_f32 v[128:129], v[24:25], s[6:7], v[128:129] op_sel:[0,1,0] op_sel_hi:[1,1,1]
	v_pk_fma_f32 v[128:129], v[26:27], s[8:9], v[128:129] op_sel_hi:[1,0,1]
	v_pk_fma_f32 v[128:129], v[28:29], s[8:9], v[128:129] op_sel:[0,1,0] op_sel_hi:[1,1,1]
	v_pk_fma_f32 v[128:129], v[30:31], s[10:11], v[128:129] op_sel_hi:[1,0,1]
	v_pk_fma_f32 v[128:129], v[32:33], s[10:11], v[128:129] op_sel:[0,1,0] op_sel_hi:[1,1,1]
	v_pk_fma_f32 v[128:129], v[34:35], s[12:13], v[128:129] op_sel_hi:[1,0,1]
	v_pk_fma_f32 v[128:129], v[36:37], s[12:13], v[128:129] op_sel:[0,1,0] op_sel_hi:[1,1,1]
	v_pk_fma_f32 v[128:129], v[38:39], s[14:15], v[128:129] op_sel_hi:[1,0,1]
	v_pk_fma_f32 v[128:129], v[40:41], s[14:15], v[128:129] op_sel:[0,1,0] op_sel_hi:[1,1,1]
	s_add_u32 s48, s48, 0x80
	s_addc_u32 s49, s49, 0
	s_load_dwordx16 s[0:15], s[48:49], 0x0
	v_pk_fma_f32 v[130:131], v[42:43], s[64:65], v[76:77] op_sel_hi:[1,0,1]
	v_pk_fma_f32 v[130:131], v[44:45], s[64:65], v[130:131] op_sel:[0,1,0] op_sel_hi:[1,1,1]
	v_pk_fma_f32 v[130:131], v[46:47], s[66:67], v[130:131] op_sel_hi:[1,0,1]
	v_pk_fma_f32 v[130:131], v[48:49], s[66:67], v[130:131] op_sel:[0,1,0] op_sel_hi:[1,1,1]
	v_pk_fma_f32 v[130:131], v[50:51], s[68:69], v[130:131] op_sel_hi:[1,0,1]
	v_pk_fma_f32 v[130:131], v[52:53], s[68:69], v[130:131] op_sel:[0,1,0] op_sel_hi:[1,1,1]
	v_pk_fma_f32 v[130:131], v[54:55], s[70:71], v[130:131] op_sel_hi:[1,0,1]
	v_pk_fma_f32 v[130:131], v[56:57], s[70:71], v[130:131] op_sel:[0,1,0] op_sel_hi:[1,1,1]
	v_pk_fma_f32 v[130:131], v[58:59], s[72:73], v[130:131] op_sel_hi:[1,0,1]
	v_pk_fma_f32 v[130:131], v[60:61], s[72:73], v[130:131] op_sel:[0,1,0] op_sel_hi:[1,1,1]
	v_pk_fma_f32 v[130:131], v[62:63], s[74:75], v[130:131] op_sel_hi:[1,0,1]
	v_pk_fma_f32 v[130:131], v[64:65], s[74:75], v[130:131] op_sel:[0,1,0] op_sel_hi:[1,1,1]
	v_pk_fma_f32 v[130:131], v[66:67], s[76:77], v[130:131] op_sel_hi:[1,0,1]
	v_pk_fma_f32 v[130:131], v[68:69], s[76:77], v[130:131] op_sel:[0,1,0] op_sel_hi:[1,1,1]
	v_pk_fma_f32 v[130:131], v[70:71], s[78:79], v[130:131] op_sel_hi:[1,0,1]
	v_pk_fma_f32 v[130:131], v[72:73], s[78:79], v[130:131] op_sel:[0,1,0] op_sel_hi:[1,1,1]
	s_load_dwordx16 s[64:79], s[48:49], 0x40
	v_mul_f32_e64 v132, |v128|, s33
	v_mul_f32_e64 v133, |v129|, s33
	v_mul_f32_e64 v134, |v130|, s33
	v_mul_f32_e64 v135, |v131|, s33
	v_exp_f32_e32 v132, v132
	v_exp_f32_e32 v133, v133
	v_exp_f32_e32 v134, v134
	v_exp_f32_e32 v135, v135
	v_pk_add_f32 v[132:133], v[132:133], 1.0 op_sel_hi:[1,0]
	v_pk_add_f32 v[134:135], v[134:135], 1.0 op_sel_hi:[1,0]
	v_log_f32_e32 v136, v132
	v_log_f32_e32 v137, v133
	v_log_f32_e32 v138, v134
	v_log_f32_e32 v139, v135
	v_pk_mul_f32 v[140:141], v[136:137], s[34:35] op_sel:[0,1] op_sel_hi:[1,1]
	v_pk_mul_f32 v[142:143], v[138:139], s[34:35] op_sel:[0,1] op_sel_hi:[1,1]
	v_pk_fma_f32 v[144:145], v[136:137], s[34:35], v[140:141] op_sel:[0,1,0] op_sel_hi:[1,1,1] neg_lo:[0,0,1] neg_hi:[0,0,1]
	v_pk_fma_f32 v[146:147], v[138:139], s[34:35], v[142:143] op_sel:[0,1,0] op_sel_hi:[1,1,1] neg_lo:[0,0,1] neg_hi:[0,0,1]
	v_pk_fma_f32 v[144:145], v[136:137], s[36:37], v[144:145] op_sel_hi:[1,0,1]
	v_pk_fma_f32 v[146:147], v[138:139], s[36:37], v[146:147] op_sel_hi:[1,0,1]
	v_pk_fma_f32 v[144:145], v[136:137], s[34:35], v[144:145] op_sel:[0,1,0] op_sel_hi:[1,1,1]
	v_pk_fma_f32 v[146:147], v[138:139], s[34:35], v[146:147] op_sel:[0,1,0] op_sel_hi:[1,1,1]
	v_min_f32_e32 v128, 0, v128
	v_min_f32_e32 v129, 0, v129
	v_min_f32_e32 v130, 0, v130
	v_min_f32_e32 v131, 0, v131
	v_pk_add_f32 v[128:129], v[128:129], v[144:145] neg_lo:[0,1] neg_hi:[0,1]
	v_pk_add_f32 v[130:131], v[130:131], v[146:147] neg_lo:[0,1] neg_hi:[0,1]
	v_pk_mul_f32 v[106:107], v[128:129], s[36:37] op_sel:[0,1] op_sel_hi:[1,1]
	v_pk_mul_f32 v[122:123], v[130:131], s[36:37] op_sel:[0,1] op_sel_hi:[1,1]
	s_waitcnt lgkmcnt(0)
	v_pk_fma_f32 v[128:129], v[10:11], s[0:1], v[74:75] op_sel_hi:[1,0,1]
	v_pk_fma_f32 v[128:129], v[12:13], s[0:1], v[128:129] op_sel:[0,1,0] op_sel_hi:[1,1,1]
	v_pk_fma_f32 v[128:129], v[14:15], s[2:3], v[128:129] op_sel_hi:[1,0,1]
	v_pk_fma_f32 v[128:129], v[16:17], s[2:3], v[128:129] op_sel:[0,1,0] op_sel_hi:[1,1,1]
	v_pk_fma_f32 v[128:129], v[18:19], s[4:5], v[128:129] op_sel_hi:[1,0,1]
	v_pk_fma_f32 v[128:129], v[20:21], s[4:5], v[128:129] op_sel:[0,1,0] op_sel_hi:[1,1,1]
	v_pk_fma_f32 v[128:129], v[22:23], s[6:7], v[128:129] op_sel_hi:[1,0,1]
	v_pk_fma_f32 v[128:129], v[24:25], s[6:7], v[128:129] op_sel:[0,1,0] op_sel_hi:[1,1,1]
	v_pk_fma_f32 v[128:129], v[26:27], s[8:9], v[128:129] op_sel_hi:[1,0,1]
	v_pk_fma_f32 v[128:129], v[28:29], s[8:9], v[128:129] op_sel:[0,1,0] op_sel_hi:[1,1,1]
	v_pk_fma_f32 v[128:129], v[30:31], s[10:11], v[128:129] op_sel_hi:[1,0,1]
	v_pk_fma_f32 v[128:129], v[32:33], s[10:11], v[128:129] op_sel:[0,1,0] op_sel_hi:[1,1,1]
	v_pk_fma_f32 v[128:129], v[34:35], s[12:13], v[128:129] op_sel_hi:[1,0,1]
	v_pk_fma_f32 v[128:129], v[36:37], s[12:13], v[128:129] op_sel:[0,1,0] op_sel_hi:[1,1,1]
	v_pk_fma_f32 v[128:129], v[38:39], s[14:15], v[128:129] op_sel_hi:[1,0,1]
	v_pk_fma_f32 v[128:129], v[40:41], s[14:15], v[128:129] op_sel:[0,1,0] op_sel_hi:[1,1,1]
	s_add_u32 s48, s48, 0x80
	s_addc_u32 s49, s49, 0
	s_load_dwordx16 s[0:15], s[48:49], 0x0
	v_pk_fma_f32 v[130:131], v[42:43], s[64:65], v[76:77] op_sel_hi:[1,0,1]
	v_pk_fma_f32 v[130:131], v[44:45], s[64:65], v[130:131] op_sel:[0,1,0] op_sel_hi:[1,1,1]
	v_pk_fma_f32 v[130:131], v[46:47], s[66:67], v[130:131] op_sel_hi:[1,0,1]
	v_pk_fma_f32 v[130:131], v[48:49], s[66:67], v[130:131] op_sel:[0,1,0] op_sel_hi:[1,1,1]
	v_pk_fma_f32 v[130:131], v[50:51], s[68:69], v[130:131] op_sel_hi:[1,0,1]
	v_pk_fma_f32 v[130:131], v[52:53], s[68:69], v[130:131] op_sel:[0,1,0] op_sel_hi:[1,1,1]
	v_pk_fma_f32 v[130:131], v[54:55], s[70:71], v[130:131] op_sel_hi:[1,0,1]
	v_pk_fma_f32 v[130:131], v[56:57], s[70:71], v[130:131] op_sel:[0,1,0] op_sel_hi:[1,1,1]
	v_pk_fma_f32 v[130:131], v[58:59], s[72:73], v[130:131] op_sel_hi:[1,0,1]
	v_pk_fma_f32 v[130:131], v[60:61], s[72:73], v[130:131] op_sel:[0,1,0] op_sel_hi:[1,1,1]
	v_pk_fma_f32 v[130:131], v[62:63], s[74:75], v[130:131] op_sel_hi:[1,0,1]
	v_pk_fma_f32 v[130:131], v[64:65], s[74:75], v[130:131] op_sel:[0,1,0] op_sel_hi:[1,1,1]
	v_pk_fma_f32 v[130:131], v[66:67], s[76:77], v[130:131] op_sel_hi:[1,0,1]
	v_pk_fma_f32 v[130:131], v[68:69], s[76:77], v[130:131] op_sel:[0,1,0] op_sel_hi:[1,1,1]
	v_pk_fma_f32 v[130:131], v[70:71], s[78:79], v[130:131] op_sel_hi:[1,0,1]
	v_pk_fma_f32 v[130:131], v[72:73], s[78:79], v[130:131] op_sel:[0,1,0] op_sel_hi:[1,1,1]
	s_load_dwordx16 s[64:79], s[48:49], 0x40
	v_mul_f32_e64 v132, |v128|, s33
	v_mul_f32_e64 v133, |v129|, s33
	v_mul_f32_e64 v134, |v130|, s33
	v_mul_f32_e64 v135, |v131|, s33
	v_exp_f32_e32 v132, v132
	v_exp_f32_e32 v133, v133
	v_exp_f32_e32 v134, v134
	v_exp_f32_e32 v135, v135
	v_pk_add_f32 v[132:133], v[132:133], 1.0 op_sel_hi:[1,0]
	v_pk_add_f32 v[134:135], v[134:135], 1.0 op_sel_hi:[1,0]
	v_log_f32_e32 v136, v132
	v_log_f32_e32 v137, v133
	v_log_f32_e32 v138, v134
	v_log_f32_e32 v139, v135
	v_pk_mul_f32 v[140:141], v[136:137], s[34:35] op_sel:[0,1] op_sel_hi:[1,1]
	v_pk_mul_f32 v[142:143], v[138:139], s[34:35] op_sel:[0,1] op_sel_hi:[1,1]
	v_pk_fma_f32 v[144:145], v[136:137], s[34:35], v[140:141] op_sel:[0,1,0] op_sel_hi:[1,1,1] neg_lo:[0,0,1] neg_hi:[0,0,1]
	v_pk_fma_f32 v[146:147], v[138:139], s[34:35], v[142:143] op_sel:[0,1,0] op_sel_hi:[1,1,1] neg_lo:[0,0,1] neg_hi:[0,0,1]
	v_pk_fma_f32 v[144:145], v[136:137], s[36:37], v[144:145] op_sel_hi:[1,0,1]
	v_pk_fma_f32 v[146:147], v[138:139], s[36:37], v[146:147] op_sel_hi:[1,0,1]
	v_pk_fma_f32 v[144:145], v[136:137], s[34:35], v[144:145] op_sel:[0,1,0] op_sel_hi:[1,1,1]
	v_pk_fma_f32 v[146:147], v[138:139], s[34:35], v[146:147] op_sel:[0,1,0] op_sel_hi:[1,1,1]
	v_min_f32_e32 v128, 0, v128
	v_min_f32_e32 v129, 0, v129
	v_min_f32_e32 v130, 0, v130
	v_min_f32_e32 v131, 0, v131
	v_pk_add_f32 v[128:129], v[128:129], v[144:145] neg_lo:[0,1] neg_hi:[0,1]
	v_pk_add_f32 v[130:131], v[130:131], v[146:147] neg_lo:[0,1] neg_hi:[0,1]
	v_pk_mul_f32 v[108:109], v[128:129], s[36:37] op_sel:[0,1] op_sel_hi:[1,1]
	v_pk_mul_f32 v[124:125], v[130:131], s[36:37] op_sel:[0,1] op_sel_hi:[1,1]
	s_waitcnt lgkmcnt(0)
	v_pk_fma_f32 v[128:129], v[10:11], s[0:1], v[74:75] op_sel_hi:[1,0,1]
	v_pk_fma_f32 v[128:129], v[12:13], s[0:1], v[128:129] op_sel:[0,1,0] op_sel_hi:[1,1,1]
	v_pk_fma_f32 v[128:129], v[14:15], s[2:3], v[128:129] op_sel_hi:[1,0,1]
	v_pk_fma_f32 v[128:129], v[16:17], s[2:3], v[128:129] op_sel:[0,1,0] op_sel_hi:[1,1,1]
	v_pk_fma_f32 v[128:129], v[18:19], s[4:5], v[128:129] op_sel_hi:[1,0,1]
	v_pk_fma_f32 v[128:129], v[20:21], s[4:5], v[128:129] op_sel:[0,1,0] op_sel_hi:[1,1,1]
	v_pk_fma_f32 v[128:129], v[22:23], s[6:7], v[128:129] op_sel_hi:[1,0,1]
	v_pk_fma_f32 v[128:129], v[24:25], s[6:7], v[128:129] op_sel:[0,1,0] op_sel_hi:[1,1,1]
	v_pk_fma_f32 v[128:129], v[26:27], s[8:9], v[128:129] op_sel_hi:[1,0,1]
	v_pk_fma_f32 v[128:129], v[28:29], s[8:9], v[128:129] op_sel:[0,1,0] op_sel_hi:[1,1,1]
	v_pk_fma_f32 v[128:129], v[30:31], s[10:11], v[128:129] op_sel_hi:[1,0,1]
	v_pk_fma_f32 v[128:129], v[32:33], s[10:11], v[128:129] op_sel:[0,1,0] op_sel_hi:[1,1,1]
	v_pk_fma_f32 v[128:129], v[34:35], s[12:13], v[128:129] op_sel_hi:[1,0,1]
	v_pk_fma_f32 v[128:129], v[36:37], s[12:13], v[128:129] op_sel:[0,1,0] op_sel_hi:[1,1,1]
	v_pk_fma_f32 v[128:129], v[38:39], s[14:15], v[128:129] op_sel_hi:[1,0,1]
	v_pk_fma_f32 v[128:129], v[40:41], s[14:15], v[128:129] op_sel:[0,1,0] op_sel_hi:[1,1,1]
	v_pk_fma_f32 v[130:131], v[42:43], s[64:65], v[76:77] op_sel_hi:[1,0,1]
	v_pk_fma_f32 v[130:131], v[44:45], s[64:65], v[130:131] op_sel:[0,1,0] op_sel_hi:[1,1,1]
	v_pk_fma_f32 v[130:131], v[46:47], s[66:67], v[130:131] op_sel_hi:[1,0,1]
	v_pk_fma_f32 v[130:131], v[48:49], s[66:67], v[130:131] op_sel:[0,1,0] op_sel_hi:[1,1,1]
	v_pk_fma_f32 v[130:131], v[50:51], s[68:69], v[130:131] op_sel_hi:[1,0,1]
	v_pk_fma_f32 v[130:131], v[52:53], s[68:69], v[130:131] op_sel:[0,1,0] op_sel_hi:[1,1,1]
	v_pk_fma_f32 v[130:131], v[54:55], s[70:71], v[130:131] op_sel_hi:[1,0,1]
	v_pk_fma_f32 v[130:131], v[56:57], s[70:71], v[130:131] op_sel:[0,1,0] op_sel_hi:[1,1,1]
	v_pk_fma_f32 v[130:131], v[58:59], s[72:73], v[130:131] op_sel_hi:[1,0,1]
	v_pk_fma_f32 v[130:131], v[60:61], s[72:73], v[130:131] op_sel:[0,1,0] op_sel_hi:[1,1,1]
	v_pk_fma_f32 v[130:131], v[62:63], s[74:75], v[130:131] op_sel_hi:[1,0,1]
	v_pk_fma_f32 v[130:131], v[64:65], s[74:75], v[130:131] op_sel:[0,1,0] op_sel_hi:[1,1,1]
	v_pk_fma_f32 v[130:131], v[66:67], s[76:77], v[130:131] op_sel_hi:[1,0,1]
	v_pk_fma_f32 v[130:131], v[68:69], s[76:77], v[130:131] op_sel:[0,1,0] op_sel_hi:[1,1,1]
	v_pk_fma_f32 v[130:131], v[70:71], s[78:79], v[130:131] op_sel_hi:[1,0,1]
	v_pk_fma_f32 v[130:131], v[72:73], s[78:79], v[130:131] op_sel:[0,1,0] op_sel_hi:[1,1,1]
	v_mul_f32_e64 v132, |v128|, s33
	v_mul_f32_e64 v133, |v129|, s33
	v_mul_f32_e64 v134, |v130|, s33
	v_mul_f32_e64 v135, |v131|, s33
	v_exp_f32_e32 v132, v132
	v_exp_f32_e32 v133, v133
	v_exp_f32_e32 v134, v134
	v_exp_f32_e32 v135, v135
	v_pk_add_f32 v[132:133], v[132:133], 1.0 op_sel_hi:[1,0]
	v_pk_add_f32 v[134:135], v[134:135], 1.0 op_sel_hi:[1,0]
	v_log_f32_e32 v136, v132
	v_log_f32_e32 v137, v133
	v_log_f32_e32 v138, v134
	v_log_f32_e32 v139, v135
	v_pk_mul_f32 v[140:141], v[136:137], s[34:35] op_sel:[0,1] op_sel_hi:[1,1]
	v_pk_mul_f32 v[142:143], v[138:139], s[34:35] op_sel:[0,1] op_sel_hi:[1,1]
	v_pk_fma_f32 v[144:145], v[136:137], s[34:35], v[140:141] op_sel:[0,1,0] op_sel_hi:[1,1,1] neg_lo:[0,0,1] neg_hi:[0,0,1]
	v_pk_fma_f32 v[146:147], v[138:139], s[34:35], v[142:143] op_sel:[0,1,0] op_sel_hi:[1,1,1] neg_lo:[0,0,1] neg_hi:[0,0,1]
	v_pk_fma_f32 v[144:145], v[136:137], s[36:37], v[144:145] op_sel_hi:[1,0,1]
	v_pk_fma_f32 v[146:147], v[138:139], s[36:37], v[146:147] op_sel_hi:[1,0,1]
	v_pk_fma_f32 v[144:145], v[136:137], s[34:35], v[144:145] op_sel:[0,1,0] op_sel_hi:[1,1,1]
	v_pk_fma_f32 v[146:147], v[138:139], s[34:35], v[146:147] op_sel:[0,1,0] op_sel_hi:[1,1,1]
	v_min_f32_e32 v128, 0, v128
	v_min_f32_e32 v129, 0, v129
	v_min_f32_e32 v130, 0, v130
	v_min_f32_e32 v131, 0, v131
	v_pk_add_f32 v[128:129], v[128:129], v[144:145] neg_lo:[0,1] neg_hi:[0,1]
	v_pk_add_f32 v[130:131], v[130:131], v[146:147] neg_lo:[0,1] neg_hi:[0,1]
	v_pk_mul_f32 v[110:111], v[128:129], s[36:37] op_sel:[0,1] op_sel_hi:[1,1]
	v_pk_mul_f32 v[126:127], v[130:131], s[36:37] op_sel:[0,1] op_sel_hi:[1,1]
	v_readlane_b32 s69, v251, 49
	s_nop 3
	s_add_i32 s51, s34, s69
	s_cmpk_lt_i32 s51, 0x480
	s_cbranch_scc0 .Lp7_no_prefetch
	s_mul_hi_u32 s80, s51, 0x1c71c72
	s_mul_i32 s92, s80, 144
	s_sub_i32 s92, s51, s92
	s_mul_hi_u32 s82, s92, 0x71c71c8
	s_mul_i32 s93, s82, 36
	s_sub_i32 s81, s92, s93
	s_lshl_b32 s92, s80, 8
	s_lshl_b32 s93, s81, 6
	s_add_i32 s92, s92, s93
	s_addk_i32 s92, 0x4000
	s_lshl_b32 s94, s80, 11
	s_add_i32 s94, s94, s93
	s_addk_i32 s94, 0xff00
	s_cmp_lt_u32 s81, 4
	s_cselect_b32 s83, s92, s94
	s_lshl_b32 s92, s32, 3
	s_add_i32 s83, s83, s92
	s_lshl_b32 s95, s82, 8
	s_mul_i32 s92, s83, 0x1800
	s_add_u32 s92, s92, s95
	s_add_u32 s84, s96, s92
	s_addc_u32 s85, s97, 0
	s_lshl_b32 s92, s83, 10
	s_add_u32 s92, s92, s95
	s_add_u32 s86, s88, 0xa27d000
	s_addc_u32 s87, s89, 0
	s_add_u32 s86, s86, s92
	s_addc_u32 s87, s87, 0
	s_add_u32 s98, s86, 0x1000000
	s_addc_u32 s99, s87, 0
	s_lshl_b32 s92, s83, 7
	s_add_u32 s100, s88, 0xf1d000
	s_addc_u32 s101, s89, 0
	s_add_u32 s100, s100, s92
	s_addc_u32 s101, s101, 0
	s_lshl_b32 s95, s82, 9
	v_readlane_b32 s52, v251, 18
	v_readlane_b32 s53, v251, 19
	s_nop 3
	s_add_u32 s52, s52, s95
	s_addc_u32 s53, s53, 0
	global_load_dwordx2 v[10:11], v3, s[52:53]
	global_load_dwordx2 v[12:13], v3, s[52:53] offset:2048
	s_add_u32 s52, s52, 0x1000
	s_addc_u32 s53, s53, 0
	global_load_dwordx2 v[14:15], v3, s[52:53]
	global_load_dwordx2 v[16:17], v3, s[52:53] offset:2048
	s_add_u32 s52, s52, 0x1000
	s_addc_u32 s53, s53, 0
	global_load_dwordx2 v[18:19], v3, s[52:53]
	global_load_dwordx2 v[20:21], v3, s[52:53] offset:2048
	s_add_u32 s52, s52, 0x1000
	s_addc_u32 s53, s53, 0
	global_load_dwordx2 v[22:23], v3, s[52:53]
	global_load_dwordx2 v[24:25], v3, s[52:53] offset:2048
	s_add_u32 s52, s52, 0x1000
	s_addc_u32 s53, s53, 0
	global_load_dwordx2 v[26:27], v3, s[52:53]
	global_load_dwordx2 v[28:29], v3, s[52:53] offset:2048
	s_add_u32 s52, s52, 0x1000
	s_addc_u32 s53, s53, 0
	global_load_dwordx2 v[30:31], v3, s[52:53]
	global_load_dwordx2 v[32:33], v3, s[52:53] offset:2048
	s_add_u32 s52, s52, 0x1000
	s_addc_u32 s53, s53, 0
	global_load_dwordx2 v[34:35], v3, s[52:53]
	global_load_dwordx2 v[36:37], v3, s[52:53] offset:2048
	s_add_u32 s52, s52, 0x1000
	s_addc_u32 s53, s53, 0
	global_load_dwordx2 v[38:39], v3, s[52:53]
	global_load_dwordx2 v[40:41], v3, s[52:53] offset:2048
	v_readlane_b32 s52, v251, 24
	v_readlane_b32 s53, v251, 25
	s_nop 3
	s_add_u32 s52, s52, s95
	s_addc_u32 s53, s53, 0
	global_load_dwordx2 v[42:43], v3, s[52:53]
	global_load_dwordx2 v[44:45], v3, s[52:53] offset:2048
	s_add_u32 s52, s52, 0x1000
	s_addc_u32 s53, s53, 0
	global_load_dwordx2 v[46:47], v3, s[52:53]
	global_load_dwordx2 v[48:49], v3, s[52:53] offset:2048
	s_add_u32 s52, s52, 0x1000
	s_addc_u32 s53, s53, 0
	global_load_dwordx2 v[50:51], v3, s[52:53]
	global_load_dwordx2 v[52:53], v3, s[52:53] offset:2048
	s_add_u32 s52, s52, 0x1000
	s_addc_u32 s53, s53, 0
	global_load_dwordx2 v[54:55], v3, s[52:53]
	global_load_dwordx2 v[56:57], v3, s[52:53] offset:2048
	s_add_u32 s52, s52, 0x1000
	s_addc_u32 s53, s53, 0
	global_load_dwordx2 v[58:59], v3, s[52:53]
	global_load_dwordx2 v[60:61], v3, s[52:53] offset:2048
	s_add_u32 s52, s52, 0x1000
	s_addc_u32 s53, s53, 0
	global_load_dwordx2 v[62:63], v3, s[52:53]
	global_load_dwordx2 v[64:65], v3, s[52:53] offset:2048
	s_add_u32 s52, s52, 0x1000
	s_addc_u32 s53, s53, 0
	global_load_dwordx2 v[66:67], v3, s[52:53]
	global_load_dwordx2 v[68:69], v3, s[52:53] offset:2048
	s_add_u32 s52, s52, 0x1000
	s_addc_u32 s53, s53, 0
	global_load_dwordx2 v[70:71], v3, s[52:53]
	global_load_dwordx2 v[72:73], v3, s[52:53] offset:2048
	v_readlane_b32 s52, v251, 20
	v_readlane_b32 s53, v251, 21
	s_nop 3
	s_add_u32 s52, s52, s95
	s_addc_u32 s53, s53, 0
	global_load_dwordx2 v[74:75], v3, s[52:53]
	v_readlane_b32 s52, v251, 26
	v_readlane_b32 s53, v251, 27
	s_nop 3
	s_add_u32 s52, s52, s95
	s_addc_u32 s53, s53, 0
	global_load_dwordx2 v[76:77], v3, s[52:53]
	s_load_dwordx16 s[0:15], s[100:101], 0x0
	s_load_dwordx16 s[64:79], s[100:101], 0x40
	s_mov_b64 s[52:53], s[84:85]
	global_load_dword v200, v2, s[52:53] offset:1024
	s_add_u32 s52, s52, 0x1800
	s_addc_u32 s53, s53, 0
	global_load_dword v201, v2, s[52:53] offset:1024
	s_add_u32 s52, s52, 0x1800
	s_addc_u32 s53, s53, 0
	global_load_dword v202, v2, s[52:53] offset:1024
	s_add_u32 s52, s52, 0x1800
	s_addc_u32 s53, s53, 0
	global_load_dword v203, v2, s[52:53] offset:1024
	s_add_u32 s52, s52, 0x1800
	s_addc_u32 s53, s53, 0
	global_load_dword v204, v2, s[52:53] offset:1024
	s_add_u32 s52, s52, 0x1800
	s_addc_u32 s53, s53, 0
	global_load_dword v205, v2, s[52:53] offset:1024
	s_add_u32 s52, s52, 0x1800
	s_addc_u32 s53, s53, 0
	global_load_dword v206, v2, s[52:53] offset:1024
	s_add_u32 s52, s52, 0x1800
	s_addc_u32 s53, s53, 0
	global_load_dword v207, v2, s[52:53] offset:1024
	s_cmp_lt_u32 s81, 4
	s_cbranch_scc1 .Lp7_noq_load_next
	s_mov_b64 s[52:53], s[84:85]
	global_load_dword v208, v2, s[52:53]
	s_add_u32 s52, s52, 0x1800
	s_addc_u32 s53, s53, 0
	global_load_dword v209, v2, s[52:53]
	s_add_u32 s52, s52, 0x1800
	s_addc_u32 s53, s53, 0
	global_load_dword v210, v2, s[52:53]
	s_add_u32 s52, s52, 0x1800
	s_addc_u32 s53, s53, 0
	global_load_dword v211, v2, s[52:53]
	s_add_u32 s52, s52, 0x1800
	s_addc_u32 s53, s53, 0
	global_load_dword v212, v2, s[52:53]
	s_add_u32 s52, s52, 0x1800
	s_addc_u32 s53, s53, 0
	global_load_dword v213, v2, s[52:53]
	s_add_u32 s52, s52, 0x1800
	s_addc_u32 s53, s53, 0
	global_load_dword v214, v2, s[52:53]
	s_add_u32 s52, s52, 0x1800
	s_addc_u32 s53, s53, 0
	global_load_dword v215, v2, s[52:53]
.Lp7_noq_load_next:
.Lp7_no_prefetch:
	v_pk_add_f32 v[98:99], v[98:99], v[96:97]
	v_pk_add_f32 v[100:101], v[100:101], v[98:99]
	v_pk_add_f32 v[102:103], v[102:103], v[100:101]
	v_pk_add_f32 v[104:105], v[104:105], v[102:103]
	v_pk_add_f32 v[106:107], v[106:107], v[104:105]
	v_pk_add_f32 v[108:109], v[108:109], v[106:107]
	v_pk_add_f32 v[110:111], v[110:111], v[108:109]
	v_pk_add_f32 v[124:125], v[124:125], v[126:127]
	v_pk_add_f32 v[122:123], v[122:123], v[124:125]
	v_pk_add_f32 v[120:121], v[120:121], v[122:123]
	v_pk_add_f32 v[118:119], v[118:119], v[120:121]
	v_pk_add_f32 v[116:117], v[116:117], v[118:119]
	v_pk_add_f32 v[114:115], v[114:115], v[116:117]
	v_pk_add_f32 v[112:113], v[112:113], v[114:115]
	s_lshl_b32 s92, s50, 13
	s_lshl_b32 s93, s32, 9
	s_add_i32 s93, s93, s92
	v_add_u32_e32 v184, s93, v3
	v_add_u32_e32 v185, s92, v3
	ds_write_b64 v184, v[110:111]
	ds_write_b64 v184, v[112:113] offset:4096
	s_waitcnt lgkmcnt(0)
	s_barrier
	ds_read_b64 v[152:153], v185 offset:0
	ds_read_b64 v[154:155], v185 offset:512
	ds_read_b64 v[156:157], v185 offset:1024
	ds_read_b64 v[158:159], v185 offset:1536
	ds_read_b64 v[160:161], v185 offset:2048
	ds_read_b64 v[162:163], v185 offset:2560
	ds_read_b64 v[164:165], v185 offset:3072
	ds_read_b64 v[166:167], v185 offset:3584
	ds_read_b64 v[168:169], v185 offset:4096
	ds_read_b64 v[170:171], v185 offset:4608
	ds_read_b64 v[172:173], v185 offset:5120
	ds_read_b64 v[174:175], v185 offset:5632
	ds_read_b64 v[176:177], v185 offset:6144
	ds_read_b64 v[178:179], v185 offset:6656
	ds_read_b64 v[180:181], v185 offset:7168
	ds_read_b64 v[182:183], v185 offset:7680
	v_mov_b32_e32 v132, 0
	v_mov_b32_e32 v133, 0
	v_mov_b32_e32 v134, 0
	v_mov_b32_e32 v135, 0
	s_waitcnt lgkmcnt(0)
	s_cmp_le_u32 s32, 0
	s_cbranch_scc1 .Lp7_offf_done
	v_add_f32_e32 v132, v132, v152
	v_add_f32_e32 v133, v133, v153
	s_cmp_le_u32 s32, 1
	s_cbranch_scc1 .Lp7_offf_done
	v_add_f32_e32 v132, v132, v154
	v_add_f32_e32 v133, v133, v155
	s_cmp_le_u32 s32, 2
	s_cbranch_scc1 .Lp7_offf_done
	v_add_f32_e32 v132, v132, v156
	v_add_f32_e32 v133, v133, v157
	s_cmp_le_u32 s32, 3
	s_cbranch_scc1 .Lp7_offf_done
	v_add_f32_e32 v132, v132, v158
	v_add_f32_e32 v133, v133, v159
	s_cmp_le_u32 s32, 4
	s_cbranch_scc1 .Lp7_offf_done
	v_add_f32_e32 v132, v132, v160
	v_add_f32_e32 v133, v133, v161
	s_cmp_le_u32 s32, 5
	s_cbranch_scc1 .Lp7_offf_done
	v_add_f32_e32 v132, v132, v162
	v_add_f32_e32 v133, v133, v163
	s_cmp_le_u32 s32, 6
	s_cbranch_scc1 .Lp7_offf_done
	v_add_f32_e32 v132, v132, v164
	v_add_f32_e32 v133, v133, v165

.Lp7_dec_done:
	s_mov_b64 s[52:53], s[42:43]
	s_mov_b64 s[54:55], s[46:47]
	v_pk_add_f32 v[136:137], v[96:97], v[132:133]
	v_pk_add_f32 v[138:139], v[112:113], v[134:135]
	v_pk_mul_f32 v[136:137], v[136:137], s[32:33] op_sel:[0,1] op_sel_hi:[1,1]
	v_pk_mul_f32 v[138:139], v[138:139], s[32:33] op_sel:[0,1] op_sel_hi:[1,1]
	v_exp_f32_e32 v136, v136
	v_exp_f32_e32 v137, v137
	v_exp_f32_e32 v138, v138
	v_exp_f32_e32 v139, v139
	v_lshlrev_b32_e32 v140, 16, v80
	v_and_b32_e32 v141, 0xffff0000, v80
	v_pk_mul_f32 v[136:137], v[140:141], v[136:137]
	v_pk_mul_f32 v[138:139], v[140:141], v[138:139]
	v_cvt_pk_bf16_f32 v142, v136, v137
	v_cvt_pk_bf16_f32 v143, v138, v139
	global_store_dword v2, v142, s[52:53] offset:1024
	global_store_dword v2, v143, s[54:55]
	s_add_u32 s52, s52, 0x1800
	s_addc_u32 s53, s53, 0
	s_add_u32 s54, s54, 0x400
	s_addc_u32 s55, s55, 0
	v_pk_add_f32 v[136:137], v[98:99], v[132:133]
	v_pk_add_f32 v[138:139], v[114:115], v[134:135]
	v_pk_mul_f32 v[136:137], v[136:137], s[32:33] op_sel:[0,1] op_sel_hi:[1,1]
	v_pk_mul_f32 v[138:139], v[138:139], s[32:33] op_sel:[0,1] op_sel_hi:[1,1]
	v_exp_f32_e32 v136, v136
	v_exp_f32_e32 v137, v137
	v_exp_f32_e32 v138, v138
	v_exp_f32_e32 v139, v139
	v_lshlrev_b32_e32 v140, 16, v81
	v_and_b32_e32 v141, 0xffff0000, v81
	v_pk_mul_f32 v[136:137], v[140:141], v[136:137]
	v_pk_mul_f32 v[138:139], v[140:141], v[138:139]
	v_cvt_pk_bf16_f32 v142, v136, v137
	v_cvt_pk_bf16_f32 v143, v138, v139
	global_store_dword v2, v142, s[52:53] offset:1024
	global_store_dword v2, v143, s[54:55]
	s_add_u32 s52, s52, 0x1800
	s_addc_u32 s53, s53, 0
	s_add_u32 s54, s54, 0x400
	s_addc_u32 s55, s55, 0
	v_pk_add_f32 v[136:137], v[100:101], v[132:133]
	v_pk_add_f32 v[138:139], v[116:117], v[134:135]
	v_pk_mul_f32 v[136:137], v[136:137], s[32:33] op_sel:[0,1] op_sel_hi:[1,1]
	v_pk_mul_f32 v[138:139], v[138:139], s[32:33] op_sel:[0,1] op_sel_hi:[1,1]
	v_exp_f32_e32 v136, v136
	v_exp_f32_e32 v137, v137
	v_exp_f32_e32 v138, v138
	v_exp_f32_e32 v139, v139
	v_lshlrev_b32_e32 v140, 16, v82
	v_and_b32_e32 v141, 0xffff0000, v82
	v_pk_mul_f32 v[136:137], v[140:141], v[136:137]
	v_pk_mul_f32 v[138:139], v[140:141], v[138:139]
	v_cvt_pk_bf16_f32 v142, v136, v137
	v_cvt_pk_bf16_f32 v143, v138, v139
	global_store_dword v2, v142, s[52:53] offset:1024
	global_store_dword v2, v143, s[54:55]
	s_add_u32 s52, s52, 0x1800
	s_addc_u32 s53, s53, 0
	s_add_u32 s54, s54, 0x400
	s_addc_u32 s55, s55, 0
	v_pk_add_f32 v[136:137], v[102:103], v[132:133]
	v_pk_add_f32 v[138:139], v[118:119], v[134:135]
	v_pk_mul_f32 v[136:137], v[136:137], s[32:33] op_sel:[0,1] op_sel_hi:[1,1]
	v_pk_mul_f32 v[138:139], v[138:139], s[32:33] op_sel:[0,1] op_sel_hi:[1,1]
	v_exp_f32_e32 v136, v136
	v_exp_f32_e32 v137, v137
	v_exp_f32_e32 v138, v138
	v_exp_f32_e32 v139, v139
	v_lshlrev_b32_e32 v140, 16, v83
	v_and_b32_e32 v141, 0xffff0000, v83
	v_pk_mul_f32 v[136:137], v[140:141], v[136:137]
	v_pk_mul_f32 v[138:139], v[140:141], v[138:139]
	v_cvt_pk_bf16_f32 v142, v136, v137
	v_cvt_pk_bf16_f32 v143, v138, v139
	global_store_dword v2, v142, s[52:53] offset:1024
	global_store_dword v2, v143, s[54:55]
	s_add_u32 s52, s52, 0x1800
	s_addc_u32 s53, s53, 0
	s_add_u32 s54, s54, 0x400
	s_addc_u32 s55, s55, 0
	v_pk_add_f32 v[136:137], v[104:105], v[132:133]
	v_pk_add_f32 v[138:139], v[120:121], v[134:135]
	v_pk_mul_f32 v[136:137], v[136:137], s[32:33] op_sel:[0,1] op_sel_hi:[1,1]
	v_pk_mul_f32 v[138:139], v[138:139], s[32:33] op_sel:[0,1] op_sel_hi:[1,1]
	v_exp_f32_e32 v136, v136
	v_exp_f32_e32 v137, v137
	v_exp_f32_e32 v138, v138
	v_exp_f32_e32 v139, v139
	v_lshlrev_b32_e32 v140, 16, v84
	v_and_b32_e32 v141, 0xffff0000, v84
	v_pk_mul_f32 v[136:137], v[140:141], v[136:137]
	v_pk_mul_f32 v[138:139], v[140:141], v[138:139]
	v_cvt_pk_bf16_f32 v142, v136, v137
	v_cvt_pk_bf16_f32 v143, v138, v139
	global_store_dword v2, v142, s[52:53] offset:1024
	global_store_dword v2, v143, s[54:55]
	s_add_u32 s52, s52, 0x1800
	s_addc_u32 s53, s53, 0
	s_add_u32 s54, s54, 0x400
	s_addc_u32 s55, s55, 0
	v_pk_add_f32 v[136:137], v[106:107], v[132:133]
	v_pk_add_f32 v[138:139], v[122:123], v[134:135]
	v_pk_mul_f32 v[136:137], v[136:137], s[32:33] op_sel:[0,1] op_sel_hi:[1,1]
	v_pk_mul_f32 v[138:139], v[138:139], s[32:33] op_sel:[0,1] op_sel_hi:[1,1]
	v_exp_f32_e32 v136, v136
	v_exp_f32_e32 v137, v137
	v_exp_f32_e32 v138, v138
	v_exp_f32_e32 v139, v139
	v_lshlrev_b32_e32 v140, 16, v85
	v_and_b32_e32 v141, 0xffff0000, v85
	v_pk_mul_f32 v[136:137], v[140:141], v[136:137]
	v_pk_mul_f32 v[138:139], v[140:141], v[138:139]
	v_cvt_pk_bf16_f32 v142, v136, v137
	v_cvt_pk_bf16_f32 v143, v138, v139
	global_store_dword v2, v142, s[52:53] offset:1024
	global_store_dword v2, v143, s[54:55]
	s_add_u32 s52, s52, 0x1800
	s_addc_u32 s53, s53, 0
	s_add_u32 s54, s54, 0x400
	s_addc_u32 s55, s55, 0
	v_pk_add_f32 v[136:137], v[108:109], v[132:133]
	v_pk_add_f32 v[138:139], v[124:125], v[134:135]
	v_pk_mul_f32 v[136:137], v[136:137], s[32:33] op_sel:[0,1] op_sel_hi:[1,1]
	v_pk_mul_f32 v[138:139], v[138:139], s[32:33] op_sel:[0,1] op_sel_hi:[1,1]
	v_exp_f32_e32 v136, v136
	v_exp_f32_e32 v137, v137
	v_exp_f32_e32 v138, v138
	v_exp_f32_e32 v139, v139
	v_lshlrev_b32_e32 v140, 16, v86
	v_and_b32_e32 v141, 0xffff0000, v86
	v_pk_mul_f32 v[136:137], v[140:141], v[136:137]
	v_pk_mul_f32 v[138:139], v[140:141], v[138:139]
	v_cvt_pk_bf16_f32 v142, v136, v137
	v_cvt_pk_bf16_f32 v143, v138, v139
	global_store_dword v2, v142, s[52:53] offset:1024
	global_store_dword v2, v143, s[54:55]
	s_add_u32 s52, s52, 0x1800
	s_addc_u32 s53, s53, 0
	s_add_u32 s54, s54, 0x400
	s_addc_u32 s55, s55, 0
	v_pk_add_f32 v[136:137], v[110:111], v[132:133]
	v_pk_add_f32 v[138:139], v[126:127], v[134:135]
	v_pk_mul_f32 v[136:137], v[136:137], s[32:33] op_sel:[0,1] op_sel_hi:[1,1]
	v_pk_mul_f32 v[138:139], v[138:139], s[32:33] op_sel:[0,1] op_sel_hi:[1,1]
	v_exp_f32_e32 v136, v136
	v_exp_f32_e32 v137, v137
	v_exp_f32_e32 v138, v138
	v_exp_f32_e32 v139, v139
	v_lshlrev_b32_e32 v140, 16, v87
	v_and_b32_e32 v141, 0xffff0000, v87
	v_pk_mul_f32 v[136:137], v[140:141], v[136:137]
	v_pk_mul_f32 v[138:139], v[140:141], v[138:139]
	v_cvt_pk_bf16_f32 v142, v136, v137
	v_cvt_pk_bf16_f32 v143, v138, v139
	global_store_dword v2, v142, s[52:53] offset:1024
	global_store_dword v2, v143, s[54:55]
	s_cmp_lt_u32 s39, 4
	s_cbranch_scc1 .Lp7_noq_store
	s_mov_b64 s[52:53], s[42:43]
	s_mov_b64 s[54:55], s[44:45]
	v_pk_add_f32 v[136:137], v[96:97], v[132:133]
	v_pk_add_f32 v[138:139], v[112:113], v[134:135]
	v_pk_mul_f32 v[136:137], v[136:137], s[32:33] op_sel:[0,1] op_sel_hi:[1,1] neg_lo:[0,1] neg_hi:[0,1]
	v_pk_mul_f32 v[138:139], v[138:139], s[32:33] op_sel:[0,1] op_sel_hi:[1,1] neg_lo:[0,1] neg_hi:[0,1]
	v_exp_f32_e32 v136, v136
	v_exp_f32_e32 v137, v137
	v_exp_f32_e32 v138, v138
	v_exp_f32_e32 v139, v139
	v_lshlrev_b32_e32 v140, 16, v88
	v_and_b32_e32 v141, 0xffff0000, v88
	v_pk_mul_f32 v[136:137], v[140:141], v[136:137]
	v_pk_mul_f32 v[138:139], v[140:141], v[138:139]
	v_cvt_pk_bf16_f32 v142, v136, v137
	v_cvt_pk_bf16_f32 v143, v138, v139
	global_store_dword v2, v142, s[52:53]
	global_store_dword v2, v143, s[54:55]
	s_add_u32 s52, s52, 0x1800
	s_addc_u32 s53, s53, 0
	s_add_u32 s54, s54, 0x400
	s_addc_u32 s55, s55, 0
	v_pk_add_f32 v[136:137], v[98:99], v[132:133]
	v_pk_add_f32 v[138:139], v[114:115], v[134:135]
	v_pk_mul_f32 v[136:137], v[136:137], s[32:33] op_sel:[0,1] op_sel_hi:[1,1] neg_lo:[0,1] neg_hi:[0,1]
	v_pk_mul_f32 v[138:139], v[138:139], s[32:33] op_sel:[0,1] op_sel_hi:[1,1] neg_lo:[0,1] neg_hi:[0,1]
	v_exp_f32_e32 v136, v136
	v_exp_f32_e32 v137, v137
	v_exp_f32_e32 v138, v138
	v_exp_f32_e32 v139, v139
	v_lshlrev_b32_e32 v140, 16, v89
	v_and_b32_e32 v141, 0xffff0000, v89
	v_pk_mul_f32 v[136:137], v[140:141], v[136:137]
	v_pk_mul_f32 v[138:139], v[140:141], v[138:139]
	v_cvt_pk_bf16_f32 v142, v136, v137
	v_cvt_pk_bf16_f32 v143, v138, v139
	global_store_dword v2, v142, s[52:53]
	global_store_dword v2, v143, s[54:55]
	s_add_u32 s52, s52, 0x1800
	s_addc_u32 s53, s53, 0
	s_add_u32 s54, s54, 0x400
	s_addc_u32 s55, s55, 0
	v_pk_add_f32 v[136:137], v[100:101], v[132:133]
	v_pk_add_f32 v[138:139], v[116:117], v[134:135]
	v_pk_mul_f32 v[136:137], v[136:137], s[32:33] op_sel:[0,1] op_sel_hi:[1,1] neg_lo:[0,1] neg_hi:[0,1]
	v_pk_mul_f32 v[138:139], v[138:139], s[32:33] op_sel:[0,1] op_sel_hi:[1,1] neg_lo:[0,1] neg_hi:[0,1]
	v_exp_f32_e32 v136, v136
	v_exp_f32_e32 v137, v137
	v_exp_f32_e32 v138, v138
	v_exp_f32_e32 v139, v139
	v_lshlrev_b32_e32 v140, 16, v90
	v_and_b32_e32 v141, 0xffff0000, v90
	v_pk_mul_f32 v[136:137], v[140:141], v[136:137]
	v_pk_mul_f32 v[138:139], v[140:141], v[138:139]
	v_cvt_pk_bf16_f32 v142, v136, v137
	v_cvt_pk_bf16_f32 v143, v138, v139
	global_store_dword v2, v142, s[52:53]
	global_store_dword v2, v143, s[54:55]
	s_add_u32 s52, s52, 0x1800
	s_addc_u32 s53, s53, 0
	s_add_u32 s54, s54, 0x400
	s_addc_u32 s55, s55, 0
	v_pk_add_f32 v[136:137], v[102:103], v[132:133]
	v_pk_add_f32 v[138:139], v[118:119], v[134:135]
	v_pk_mul_f32 v[136:137], v[136:137], s[32:33] op_sel:[0,1] op_sel_hi:[1,1] neg_lo:[0,1] neg_hi:[0,1]
	v_pk_mul_f32 v[138:139], v[138:139], s[32:33] op_sel:[0,1] op_sel_hi:[1,1] neg_lo:[0,1] neg_hi:[0,1]
	v_exp_f32_e32 v136, v136
	v_exp_f32_e32 v137, v137
	v_exp_f32_e32 v138, v138
	v_exp_f32_e32 v139, v139
	v_lshlrev_b32_e32 v140, 16, v91
	v_and_b32_e32 v141, 0xffff0000, v91
	v_pk_mul_f32 v[136:137], v[140:141], v[136:137]
	v_pk_mul_f32 v[138:139], v[140:141], v[138:139]
	v_cvt_pk_bf16_f32 v142, v136, v137
	v_cvt_pk_bf16_f32 v143, v138, v139
	global_store_dword v2, v142, s[52:53]
	global_store_dword v2, v143, s[54:55]
	s_add_u32 s52, s52, 0x1800
	s_addc_u32 s53, s53, 0
	s_add_u32 s54, s54, 0x400
	s_addc_u32 s55, s55, 0
	v_pk_add_f32 v[136:137], v[104:105], v[132:133]
	v_pk_add_f32 v[138:139], v[120:121], v[134:135]
	v_pk_mul_f32 v[136:137], v[136:137], s[32:33] op_sel:[0,1] op_sel_hi:[1,1] neg_lo:[0,1] neg_hi:[0,1]
	v_pk_mul_f32 v[138:139], v[138:139], s[32:33] op_sel:[0,1] op_sel_hi:[1,1] neg_lo:[0,1] neg_hi:[0,1]
	v_exp_f32_e32 v136, v136
	v_exp_f32_e32 v137, v137
	v_exp_f32_e32 v138, v138
	v_exp_f32_e32 v139, v139
	v_lshlrev_b32_e32 v140, 16, v92
	v_and_b32_e32 v141, 0xffff0000, v92
	v_pk_mul_f32 v[136:137], v[140:141], v[136:137]
	v_pk_mul_f32 v[138:139], v[140:141], v[138:139]
	v_cvt_pk_bf16_f32 v142, v136, v137
	v_cvt_pk_bf16_f32 v143, v138, v139
	global_store_dword v2, v142, s[52:53]
	global_store_dword v2, v143, s[54:55]
	s_add_u32 s52, s52, 0x1800
	s_addc_u32 s53, s53, 0
	s_add_u32 s54, s54, 0x400
	s_addc_u32 s55, s55, 0
	v_pk_add_f32 v[136:137], v[106:107], v[132:133]
	v_pk_add_f32 v[138:139], v[122:123], v[134:135]
	v_pk_mul_f32 v[136:137], v[136:137], s[32:33] op_sel:[0,1] op_sel_hi:[1,1] neg_lo:[0,1] neg_hi:[0,1]
	v_pk_mul_f32 v[138:139], v[138:139], s[32:33] op_sel:[0,1] op_sel_hi:[1,1] neg_lo:[0,1] neg_hi:[0,1]
	v_exp_f32_e32 v136, v136
	v_exp_f32_e32 v137, v137
	v_exp_f32_e32 v138, v138
	v_exp_f32_e32 v139, v139
	v_lshlrev_b32_e32 v140, 16, v93
	v_and_b32_e32 v141, 0xffff0000, v93
	v_pk_mul_f32 v[136:137], v[140:141], v[136:137]
	v_pk_mul_f32 v[138:139], v[140:141], v[138:139]
	v_cvt_pk_bf16_f32 v142, v136, v137
	v_cvt_pk_bf16_f32 v143, v138, v139
	global_store_dword v2, v142, s[52:53]
	global_store_dword v2, v143, s[54:55]
	s_add_u32 s52, s52, 0x1800
	s_addc_u32 s53, s53, 0
	s_add_u32 s54, s54, 0x400
	s_addc_u32 s55, s55, 0
	v_pk_add_f32 v[136:137], v[108:109], v[132:133]
	v_pk_add_f32 v[138:139], v[124:125], v[134:135]
	v_pk_mul_f32 v[136:137], v[136:137], s[32:33] op_sel:[0,1] op_sel_hi:[1,1] neg_lo:[0,1] neg_hi:[0,1]
	v_pk_mul_f32 v[138:139], v[138:139], s[32:33] op_sel:[0,1] op_sel_hi:[1,1] neg_lo:[0,1] neg_hi:[0,1]
	v_exp_f32_e32 v136, v136
	v_exp_f32_e32 v137, v137
	v_exp_f32_e32 v138, v138
	v_exp_f32_e32 v139, v139
	v_lshlrev_b32_e32 v140, 16, v94
	v_and_b32_e32 v141, 0xffff0000, v94
	v_pk_mul_f32 v[136:137], v[140:141], v[136:137]
	v_pk_mul_f32 v[138:139], v[140:141], v[138:139]
	v_cvt_pk_bf16_f32 v142, v136, v137
	v_cvt_pk_bf16_f32 v143, v138, v139
	global_store_dword v2, v142, s[52:53]
	global_store_dword v2, v143, s[54:55]
	s_add_u32 s52, s52, 0x1800
	s_addc_u32 s53, s53, 0
	s_add_u32 s54, s54, 0x400
	s_addc_u32 s55, s55, 0
	v_pk_add_f32 v[136:137], v[110:111], v[132:133]
	v_pk_add_f32 v[138:139], v[126:127], v[134:135]
	v_pk_mul_f32 v[136:137], v[136:137], s[32:33] op_sel:[0,1] op_sel_hi:[1,1] neg_lo:[0,1] neg_hi:[0,1]
	v_pk_mul_f32 v[138:139], v[138:139], s[32:33] op_sel:[0,1] op_sel_hi:[1,1] neg_lo:[0,1] neg_hi:[0,1]
	v_exp_f32_e32 v136, v136
	v_exp_f32_e32 v137, v137
	v_exp_f32_e32 v138, v138
	v_exp_f32_e32 v139, v139
	v_lshlrev_b32_e32 v140, 16, v95
	v_and_b32_e32 v141, 0xffff0000, v95
	v_pk_mul_f32 v[136:137], v[140:141], v[136:137]
	v_pk_mul_f32 v[138:139], v[140:141], v[138:139]
	v_cvt_pk_bf16_f32 v142, v136, v137
	v_cvt_pk_bf16_f32 v143, v138, v139
	global_store_dword v2, v142, s[52:53]
	global_store_dword v2, v143, s[54:55]
.Lp7_noq_store:
	s_cmpk_lt_i32 s51, 0x480
	s_cbranch_scc0 .Lp7_exit
	s_mov_b32 s34, s51
	s_xor_b32 s50, s50, 1
	s_mov_b32 s38, s80
	s_mov_b32 s39, s81
	s_mov_b32 s40, s82
	s_mov_b32 s41, s83
	s_mov_b64 s[42:43], s[84:85]
	s_mov_b64 s[44:45], s[86:87]
	s_mov_b64 s[46:47], s[98:99]
	s_mov_b64 s[48:49], s[100:101]
	s_waitcnt vmcnt(16)
	s_branch .Lp7_item

.LBB0_902:
	s_or_b64 exec, exec, s[8:9]
	s_mov_b64 s[8:9], exec
	v_mbcnt_lo_u32_b32 v2, s8, 0
	v_mbcnt_hi_u32_b32 v2, s9, v2
	v_cmp_eq_u32_e32 vcc, 0, v2
	s_waitcnt vmcnt(0)
	buffer_inv sc1
	s_and_saveexec_b64 s[10:11], vcc
	s_cbranch_execz .LBB0_904
	s_bcnt1_i32_b64 s2, s[8:9]
	v_mov_b32_e32 v2, 0x2000
	v_mov_b32_e32 v3, s2
.LBB0_904:
	s_or_b64 exec, exec, s[10:11]
	s_waitcnt vmcnt(0)

.LBB0_1048:
	s_or_b64 exec, exec, s[8:9]
	s_mov_b64 s[8:9], exec
	v_mbcnt_lo_u32_b32 v2, s8, 0
	v_mbcnt_hi_u32_b32 v2, s9, v2
	v_cmp_eq_u32_e32 vcc, 0, v2
	s_waitcnt vmcnt(0)
	buffer_inv sc1
	s_and_saveexec_b64 s[10:11], vcc
	s_cbranch_execz .LBB0_1050
	s_bcnt1_i32_b64 s2, s[8:9]
	v_mov_b32_e32 v2, 0x2000
	v_mov_b32_e32 v3, s2
.LBB0_1050:
	s_or_b64 exec, exec, s[10:11]
	s_waitcnt vmcnt(0)

.LBB0_1107:
	s_or_b64 exec, exec, s[8:9]
	s_mov_b64 s[8:9], exec
	v_mbcnt_lo_u32_b32 v2, s8, 0
	v_mbcnt_hi_u32_b32 v2, s9, v2
	v_cmp_eq_u32_e32 vcc, 0, v2
	s_waitcnt vmcnt(0)
	buffer_inv sc1
	s_and_saveexec_b64 s[10:11], vcc
	s_cbranch_execz .LBB0_1109
	s_bcnt1_i32_b64 s2, s[8:9]
	v_mov_b32_e32 v2, 0x2000
	v_mov_b32_e32 v3, s2
.LBB0_1109:
	s_or_b64 exec, exec, s[10:11]
	s_waitcnt vmcnt(0)
